# in-GEMM units with a successor: leading half interleaves epilogue second half into the next unit's first peel MFMA block; trailing half runs its second half right after its realign barrier (concurrent
# speedup vs baseline: 1.0066x; 1.0066x over previous
.Lov_0:
	v_mul_f32_e32 v151, 0xbfb8aa3b, v124
	v_exp_f32_e32 v151, v151
	v_mul_f32_e32 v154, 0xbfb8aa3b, v125
	v_exp_f32_e32 v154, v154
	v_lshl_or_b32 v142, s65, 7, v146
	v_add_f32_e32 v151, 1.0, v151
	v_rcp_f32_e32 v151, v151
	v_lshl_add_u32 v150, s36, 8, v144
	v_ashrrev_i32_e32 v143, 31, v142
	v_mov_b64_e32 v[140:141], s[22:23]
	v_mul_f32_e32 v124, v124, v151
	v_mul_f32_e32 v120, v120, v124
	v_add_f32_e32 v124, 1.0, v154
	v_mul_f32_e32 v151, 0xbfb8aa3b, v126
	v_rcp_f32_e32 v124, v124
	v_exp_f32_e32 v151, v151
	v_mul_f32_e32 v154, 0xbfb8aa3b, v127
	v_exp_f32_e32 v154, v154
	v_mul_f32_e32 v124, v125, v124
	v_add_f32_e32 v125, 1.0, v151
	v_rcp_f32_e32 v125, v125
	v_add_f32_e32 v151, 1.0, v154
	v_rcp_f32_e32 v151, v151
	v_mul_f32_e32 v121, v121, v124
	v_mul_f32_e32 v124, v126, v125
	v_mul_f32_e32 v125, 0xbfb8aa3b, v116
	v_exp_f32_e32 v125, v125
	v_mul_f32_e32 v122, v122, v124
	v_mul_f32_e32 v124, v127, v151
	v_mul_f32_e32 v123, v123, v124
	v_cvt_pk_bf16_f32 v120, v120, v121
	v_cvt_pk_bf16_f32 v121, v122, v123
	v_add_f32_e32 v122, 1.0, v125
	v_rcp_f32_e32 v122, v122
	v_mul_f32_e32 v123, 0xbfb8aa3b, v117
	v_exp_f32_e32 v123, v123
	v_mad_i64_i32 v[152:153], s[44:45], v150, s64, v[140:141]
	v_lshlrev_b64 v[142:143], 1, v[142:143]
	v_lshl_add_u64 v[152:153], v[152:153], 0, v[142:143]
	v_mul_f32_e32 v116, v116, v122
	global_store_dwordx2 v[152:153], v[120:121], off
	v_mul_f32_e32 v112, v112, v116
	v_add_f32_e32 v116, 1.0, v123
	v_mul_f32_e32 v120, 0xbfb8aa3b, v118
	v_rcp_f32_e32 v116, v116
	v_exp_f32_e32 v120, v120
	v_mul_f32_e32 v121, 0xbfb8aa3b, v119
	v_exp_f32_e32 v121, v121
	v_mul_f32_e32 v116, v117, v116
	v_add_f32_e32 v117, 1.0, v120
	v_rcp_f32_e32 v117, v117
	v_add_f32_e32 v120, 1.0, v121
	v_rcp_f32_e32 v120, v120
	v_mul_f32_e32 v113, v113, v116
	v_mul_f32_e32 v116, v118, v117
	v_mul_f32_e32 v114, v114, v116
	v_mul_f32_e32 v116, v119, v120
	v_cvt_pk_bf16_f32 v112, v112, v113
	v_mul_f32_e32 v115, v115, v116
	v_cvt_pk_bf16_f32 v113, v114, v115
	global_store_dwordx2 v[152:153], v[112:113], off offset:128
	v_mul_f32_e32 v112, 0xbfb8aa3b, v108
	v_exp_f32_e32 v114, v112
	v_mul_f32_e32 v115, 0xbfb8aa3b, v109
	v_exp_f32_e32 v115, v115
	v_or_b32_e32 v112, 16, v150
	v_add_f32_e32 v114, 1.0, v114
	v_rcp_f32_e32 v114, v114
	v_mad_i64_i32 v[112:113], s[44:45], v112, s64, v[140:141]
	v_lshl_add_u64 v[112:113], v[112:113], 0, v[142:143]
	v_mul_f32_e32 v108, v108, v114
	v_mul_f32_e32 v104, v104, v108
	v_add_f32_e32 v108, 1.0, v115
	v_mul_f32_e32 v114, 0xbfb8aa3b, v110
	v_rcp_f32_e32 v108, v108
	v_exp_f32_e32 v114, v114
	v_mul_f32_e32 v115, 0xbfb8aa3b, v111
	v_exp_f32_e32 v115, v115
	v_mul_f32_e32 v108, v109, v108
	v_add_f32_e32 v109, 1.0, v114
	v_rcp_f32_e32 v109, v109
	v_add_f32_e32 v114, 1.0, v115
	v_rcp_f32_e32 v114, v114
	v_mul_f32_e32 v105, v105, v108
	v_mul_f32_e32 v108, v110, v109
	v_mul_f32_e32 v109, 0xbfb8aa3b, v100
	v_exp_f32_e32 v109, v109
	v_mul_f32_e32 v106, v106, v108
	v_mul_f32_e32 v108, v111, v114
	v_mul_f32_e32 v107, v107, v108
	v_cvt_pk_bf16_f32 v104, v104, v105
	v_cvt_pk_bf16_f32 v105, v106, v107
	v_add_f32_e32 v106, 1.0, v109
	v_rcp_f32_e32 v106, v106
	v_mul_f32_e32 v107, 0xbfb8aa3b, v101
	v_exp_f32_e32 v107, v107
	global_store_dwordx2 v[112:113], v[104:105], off
	v_mul_f32_e32 v100, v100, v106
	v_mul_f32_e32 v96, v96, v100
	v_add_f32_e32 v100, 1.0, v107
	v_mul_f32_e32 v104, 0xbfb8aa3b, v102
	v_rcp_f32_e32 v100, v100
	v_exp_f32_e32 v104, v104
	v_mul_f32_e32 v105, 0xbfb8aa3b, v103
	v_exp_f32_e32 v105, v105
	v_mul_f32_e32 v100, v101, v100
	v_add_f32_e32 v101, 1.0, v104
	v_rcp_f32_e32 v101, v101
	v_add_f32_e32 v104, 1.0, v105
	v_rcp_f32_e32 v104, v104
	v_mul_f32_e32 v97, v97, v100
	v_mul_f32_e32 v100, v102, v101
	v_mul_f32_e32 v98, v98, v100
	v_mul_f32_e32 v100, v103, v104
	v_cvt_pk_bf16_f32 v96, v96, v97
	v_mul_f32_e32 v99, v99, v100
	v_cvt_pk_bf16_f32 v97, v98, v99
	global_store_dwordx2 v[112:113], v[96:97], off offset:128
	v_mul_f32_e32 v96, 0xbfb8aa3b, v92
	v_exp_f32_e32 v98, v96
	v_mul_f32_e32 v99, 0xbfb8aa3b, v93
	v_exp_f32_e32 v99, v99
	v_or_b32_e32 v96, 32, v150
	v_add_f32_e32 v98, 1.0, v98
	v_rcp_f32_e32 v98, v98
	v_mad_i64_i32 v[96:97], s[44:45], v96, s64, v[140:141]
	v_lshl_add_u64 v[96:97], v[96:97], 0, v[142:143]
	v_mul_f32_e32 v92, v92, v98
	v_mul_f32_e32 v88, v88, v92
	v_add_f32_e32 v92, 1.0, v99
	v_mul_f32_e32 v98, 0xbfb8aa3b, v94
	v_rcp_f32_e32 v92, v92
	v_exp_f32_e32 v98, v98
	v_mul_f32_e32 v99, 0xbfb8aa3b, v95
	v_exp_f32_e32 v99, v99
	v_mul_f32_e32 v92, v93, v92
	v_add_f32_e32 v93, 1.0, v98
	v_rcp_f32_e32 v93, v93
	v_add_f32_e32 v98, 1.0, v99
	v_rcp_f32_e32 v98, v98
	v_mul_f32_e32 v89, v89, v92
	v_mul_f32_e32 v92, v94, v93
	v_mul_f32_e32 v93, 0xbfb8aa3b, v84
	v_exp_f32_e32 v93, v93
	v_mul_f32_e32 v90, v90, v92
	v_mul_f32_e32 v92, v95, v98
	v_mul_f32_e32 v91, v91, v92
	v_cvt_pk_bf16_f32 v88, v88, v89
	v_cvt_pk_bf16_f32 v89, v90, v91
	v_add_f32_e32 v90, 1.0, v93
	v_rcp_f32_e32 v90, v90
	v_mul_f32_e32 v91, 0xbfb8aa3b, v85
	v_exp_f32_e32 v91, v91
	global_store_dwordx2 v[96:97], v[88:89], off
	v_mul_f32_e32 v84, v84, v90
	v_mul_f32_e32 v80, v80, v84
	v_add_f32_e32 v84, 1.0, v91
	v_mul_f32_e32 v88, 0xbfb8aa3b, v86
	v_rcp_f32_e32 v84, v84
	v_exp_f32_e32 v88, v88
	v_mul_f32_e32 v89, 0xbfb8aa3b, v87
	v_exp_f32_e32 v89, v89
	v_mul_f32_e32 v84, v85, v84
	v_add_f32_e32 v85, 1.0, v88
	v_rcp_f32_e32 v85, v85
	v_add_f32_e32 v88, 1.0, v89
	v_rcp_f32_e32 v88, v88
	v_mul_f32_e32 v81, v81, v84
	v_mul_f32_e32 v84, v86, v85
	v_mul_f32_e32 v82, v82, v84
	v_mul_f32_e32 v84, v87, v88
	v_cvt_pk_bf16_f32 v80, v80, v81
	v_mul_f32_e32 v83, v83, v84
	v_cvt_pk_bf16_f32 v81, v82, v83
	global_store_dwordx2 v[96:97], v[80:81], off offset:128
	v_mul_f32_e32 v80, 0xbfb8aa3b, v76
	v_exp_f32_e32 v82, v80
	v_mul_f32_e32 v83, 0xbfb8aa3b, v77
	v_exp_f32_e32 v83, v83
	v_or_b32_e32 v80, 48, v150
	v_add_f32_e32 v82, 1.0, v82
	v_rcp_f32_e32 v82, v82
	v_mad_i64_i32 v[80:81], s[44:45], v80, s64, v[140:141]
	v_lshl_add_u64 v[80:81], v[80:81], 0, v[142:143]
	v_mul_f32_e32 v76, v76, v82
	v_mul_f32_e32 v72, v72, v76
	v_add_f32_e32 v76, 1.0, v83
	v_mul_f32_e32 v82, 0xbfb8aa3b, v78
	v_rcp_f32_e32 v76, v76
	v_exp_f32_e32 v82, v82
	v_mul_f32_e32 v83, 0xbfb8aa3b, v79
	v_exp_f32_e32 v83, v83
	v_mul_f32_e32 v76, v77, v76
	v_add_f32_e32 v77, 1.0, v82
	v_rcp_f32_e32 v77, v77
	v_add_f32_e32 v82, 1.0, v83
	v_rcp_f32_e32 v82, v82
	v_mul_f32_e32 v73, v73, v76
	v_mul_f32_e32 v76, v78, v77
	v_mul_f32_e32 v77, 0xbfb8aa3b, v68
	v_exp_f32_e32 v77, v77
	v_mul_f32_e32 v74, v74, v76
	v_mul_f32_e32 v76, v79, v82
	v_mul_f32_e32 v75, v75, v76
	v_cvt_pk_bf16_f32 v72, v72, v73
	v_cvt_pk_bf16_f32 v73, v74, v75
	v_add_f32_e32 v74, 1.0, v77
	v_rcp_f32_e32 v74, v74
	v_mul_f32_e32 v75, 0xbfb8aa3b, v69
	v_exp_f32_e32 v75, v75
	global_store_dwordx2 v[80:81], v[72:73], off
	v_mul_f32_e32 v68, v68, v74
	v_mul_f32_e32 v64, v64, v68
	v_add_f32_e32 v68, 1.0, v75
	v_mul_f32_e32 v72, 0xbfb8aa3b, v70
	v_rcp_f32_e32 v68, v68
	v_exp_f32_e32 v72, v72
	v_mul_f32_e32 v73, 0xbfb8aa3b, v71
	v_exp_f32_e32 v73, v73
	v_mul_f32_e32 v68, v69, v68
	v_add_f32_e32 v69, 1.0, v72
	v_rcp_f32_e32 v69, v69
	v_add_f32_e32 v72, 1.0, v73
	v_rcp_f32_e32 v72, v72
	v_mul_f32_e32 v65, v65, v68
	v_mul_f32_e32 v68, v70, v69
	v_mul_f32_e32 v66, v66, v68
	v_mul_f32_e32 v68, v71, v72
	v_cvt_pk_bf16_f32 v64, v64, v65
	v_mul_f32_e32 v67, v67, v68
	v_cvt_pk_bf16_f32 v65, v66, v67
	global_store_dwordx2 v[80:81], v[64:65], off offset:128
	v_mov_b32_e32 v216, v140
	v_mov_b32_e32 v217, v141
	v_mov_b32_e32 v218, v142
	v_mov_b32_e32 v219, v143
	v_mov_b32_e32 v220, v150
	s_andn2_b64 vcc, exec, s[0:1]
	s_cbranch_vccnz .Lov_nb_0
	s_barrier
	v_mul_f32_e32 v64, 0xbfb8aa3b, v60
	v_exp_f32_e32 v66, v64
	v_mul_f32_e32 v67, 0xbfb8aa3b, v61
	v_exp_f32_e32 v67, v67
	v_add_u32_e32 v64, 0x80, v150
	v_add_f32_e32 v66, 1.0, v66
	v_rcp_f32_e32 v66, v66
	v_mad_i64_i32 v[64:65], vcc, v64, s64, v[140:141]
	v_lshl_add_u64 v[64:65], v[64:65], 0, v[142:143]
	v_mul_f32_e32 v60, v60, v66
	v_mul_f32_e32 v56, v56, v60
	v_add_f32_e32 v60, 1.0, v67
	v_mul_f32_e32 v66, 0xbfb8aa3b, v62
	v_rcp_f32_e32 v60, v60
	v_exp_f32_e32 v66, v66
	v_mul_f32_e32 v67, 0xbfb8aa3b, v63
	v_exp_f32_e32 v67, v67
	v_mul_f32_e32 v60, v61, v60
	v_add_f32_e32 v61, 1.0, v66
	v_rcp_f32_e32 v61, v61
	v_add_f32_e32 v66, 1.0, v67
	v_rcp_f32_e32 v66, v66
	v_mul_f32_e32 v57, v57, v60
	v_mul_f32_e32 v60, v62, v61
	v_mul_f32_e32 v61, 0xbfb8aa3b, v52
	v_exp_f32_e32 v61, v61
	v_mul_f32_e32 v58, v58, v60
	v_mul_f32_e32 v60, v63, v66
	v_mul_f32_e32 v59, v59, v60
	v_cvt_pk_bf16_f32 v56, v56, v57
	v_cvt_pk_bf16_f32 v57, v58, v59
	v_add_f32_e32 v58, 1.0, v61
	v_rcp_f32_e32 v58, v58
	v_mul_f32_e32 v59, 0xbfb8aa3b, v53
	v_exp_f32_e32 v59, v59
	global_store_dwordx2 v[64:65], v[56:57], off
	v_mul_f32_e32 v52, v52, v58
	v_mul_f32_e32 v48, v48, v52
	v_add_f32_e32 v52, 1.0, v59
	v_mul_f32_e32 v56, 0xbfb8aa3b, v54
	v_rcp_f32_e32 v52, v52
	v_exp_f32_e32 v56, v56
	v_mul_f32_e32 v57, 0xbfb8aa3b, v55
	v_exp_f32_e32 v57, v57
	v_mul_f32_e32 v52, v53, v52
	v_add_f32_e32 v53, 1.0, v56
	v_rcp_f32_e32 v53, v53
	v_add_f32_e32 v56, 1.0, v57
	v_rcp_f32_e32 v56, v56
	v_mul_f32_e32 v49, v49, v52
	v_mul_f32_e32 v52, v54, v53
	v_mul_f32_e32 v50, v50, v52
	v_mul_f32_e32 v52, v55, v56
	v_cvt_pk_bf16_f32 v48, v48, v49
	v_mul_f32_e32 v51, v51, v52
	v_cvt_pk_bf16_f32 v49, v50, v51
	global_store_dwordx2 v[64:65], v[48:49], off offset:128
	v_mul_f32_e32 v48, 0xbfb8aa3b, v44
	v_exp_f32_e32 v50, v48
	v_mul_f32_e32 v51, 0xbfb8aa3b, v45
	v_exp_f32_e32 v51, v51
	v_add_u32_e32 v48, 0x90, v150
	v_add_f32_e32 v50, 1.0, v50
	v_rcp_f32_e32 v50, v50
	v_mad_i64_i32 v[48:49], vcc, v48, s64, v[140:141]
	v_lshl_add_u64 v[48:49], v[48:49], 0, v[142:143]
	v_mul_f32_e32 v44, v44, v50
	v_mul_f32_e32 v40, v40, v44
	v_add_f32_e32 v44, 1.0, v51
	v_mul_f32_e32 v50, 0xbfb8aa3b, v46
	v_rcp_f32_e32 v44, v44
	v_exp_f32_e32 v50, v50
	v_mul_f32_e32 v51, 0xbfb8aa3b, v47
	v_exp_f32_e32 v51, v51
	v_mul_f32_e32 v44, v45, v44
	v_add_f32_e32 v45, 1.0, v50
	v_rcp_f32_e32 v45, v45
	v_add_f32_e32 v50, 1.0, v51
	v_rcp_f32_e32 v50, v50
	v_mul_f32_e32 v41, v41, v44
	v_mul_f32_e32 v44, v46, v45
	v_mul_f32_e32 v45, 0xbfb8aa3b, v36
	v_exp_f32_e32 v45, v45
	v_mul_f32_e32 v42, v42, v44
	v_mul_f32_e32 v44, v47, v50
	v_mul_f32_e32 v43, v43, v44
	v_cvt_pk_bf16_f32 v40, v40, v41
	v_cvt_pk_bf16_f32 v41, v42, v43
	v_add_f32_e32 v42, 1.0, v45
	v_rcp_f32_e32 v42, v42
	v_mul_f32_e32 v43, 0xbfb8aa3b, v37
	v_exp_f32_e32 v43, v43
	global_store_dwordx2 v[48:49], v[40:41], off
	v_mul_f32_e32 v36, v36, v42
	v_mul_f32_e32 v32, v32, v36
	v_add_f32_e32 v36, 1.0, v43
	v_mul_f32_e32 v40, 0xbfb8aa3b, v38
	v_rcp_f32_e32 v36, v36
	v_exp_f32_e32 v40, v40
	v_mul_f32_e32 v41, 0xbfb8aa3b, v39
	v_exp_f32_e32 v41, v41
	v_mul_f32_e32 v36, v37, v36
	v_add_f32_e32 v37, 1.0, v40
	v_rcp_f32_e32 v37, v37
	v_add_f32_e32 v40, 1.0, v41
	v_rcp_f32_e32 v40, v40
	v_mul_f32_e32 v33, v33, v36
	v_mul_f32_e32 v36, v38, v37
	v_mul_f32_e32 v34, v34, v36
	v_mul_f32_e32 v36, v39, v40
	v_cvt_pk_bf16_f32 v32, v32, v33
	v_mul_f32_e32 v35, v35, v36
	v_cvt_pk_bf16_f32 v33, v34, v35
	global_store_dwordx2 v[48:49], v[32:33], off offset:128
	v_mul_f32_e32 v32, 0xbfb8aa3b, v28
	v_exp_f32_e32 v34, v32
	v_mul_f32_e32 v35, 0xbfb8aa3b, v29
	v_exp_f32_e32 v35, v35
	v_add_u32_e32 v32, 0xa0, v150
	v_add_f32_e32 v34, 1.0, v34
	v_rcp_f32_e32 v34, v34
	v_mad_i64_i32 v[32:33], vcc, v32, s64, v[140:141]
	v_lshl_add_u64 v[32:33], v[32:33], 0, v[142:143]
	v_mul_f32_e32 v28, v28, v34
	v_mul_f32_e32 v24, v24, v28
	v_add_f32_e32 v28, 1.0, v35
	v_mul_f32_e32 v34, 0xbfb8aa3b, v30
	v_rcp_f32_e32 v28, v28
	v_exp_f32_e32 v34, v34
	v_mul_f32_e32 v35, 0xbfb8aa3b, v31
	v_exp_f32_e32 v35, v35
	v_mul_f32_e32 v28, v29, v28
	v_add_f32_e32 v29, 1.0, v34
	v_rcp_f32_e32 v29, v29
	v_add_f32_e32 v34, 1.0, v35
	v_rcp_f32_e32 v34, v34
	v_mul_f32_e32 v25, v25, v28
	v_mul_f32_e32 v28, v30, v29
	v_mul_f32_e32 v29, 0xbfb8aa3b, v20
	v_exp_f32_e32 v29, v29
	v_mul_f32_e32 v26, v26, v28
	v_mul_f32_e32 v28, v31, v34
	v_mul_f32_e32 v27, v27, v28
	v_cvt_pk_bf16_f32 v24, v24, v25
	v_cvt_pk_bf16_f32 v25, v26, v27
	v_add_f32_e32 v26, 1.0, v29
	v_rcp_f32_e32 v26, v26
	v_mul_f32_e32 v27, 0xbfb8aa3b, v21
	v_exp_f32_e32 v27, v27
	global_store_dwordx2 v[32:33], v[24:25], off
	v_mul_f32_e32 v20, v20, v26
	v_mul_f32_e32 v16, v16, v20
	v_add_f32_e32 v20, 1.0, v27
	v_mul_f32_e32 v24, 0xbfb8aa3b, v22
	v_rcp_f32_e32 v20, v20
	v_exp_f32_e32 v24, v24
	v_mul_f32_e32 v25, 0xbfb8aa3b, v23
	v_exp_f32_e32 v25, v25
	v_mul_f32_e32 v20, v21, v20
	v_add_f32_e32 v21, 1.0, v24
	v_rcp_f32_e32 v21, v21
	v_add_f32_e32 v24, 1.0, v25
	v_rcp_f32_e32 v24, v24
	v_mul_f32_e32 v17, v17, v20
	v_mul_f32_e32 v20, v22, v21
	v_mul_f32_e32 v18, v18, v20
	v_mul_f32_e32 v20, v23, v24
	v_cvt_pk_bf16_f32 v16, v16, v17
	v_mul_f32_e32 v19, v19, v20
	v_cvt_pk_bf16_f32 v17, v18, v19
	global_store_dwordx2 v[32:33], v[16:17], off offset:128
	v_mul_f32_e32 v16, 0xbfb8aa3b, v12
	v_exp_f32_e32 v18, v16
	v_mul_f32_e32 v19, 0xbfb8aa3b, v13
	v_exp_f32_e32 v19, v19
	v_add_u32_e32 v16, 0xb0, v150
	v_add_f32_e32 v18, 1.0, v18
	v_rcp_f32_e32 v18, v18
	v_mad_i64_i32 v[16:17], vcc, v16, s64, v[140:141]
	v_lshl_add_u64 v[16:17], v[16:17], 0, v[142:143]
	v_mul_f32_e32 v12, v12, v18
	v_mul_f32_e32 v8, v8, v12
	v_add_f32_e32 v12, 1.0, v19
	v_mul_f32_e32 v18, 0xbfb8aa3b, v14
	v_rcp_f32_e32 v12, v12
	v_exp_f32_e32 v18, v18
	v_mul_f32_e32 v19, 0xbfb8aa3b, v15
	v_exp_f32_e32 v19, v19
	v_mul_f32_e32 v12, v13, v12
	v_add_f32_e32 v13, 1.0, v18
	v_rcp_f32_e32 v13, v13
	v_add_f32_e32 v18, 1.0, v19
	v_rcp_f32_e32 v18, v18
	v_mul_f32_e32 v9, v9, v12
	v_mul_f32_e32 v12, v14, v13
	v_mul_f32_e32 v13, 0xbfb8aa3b, v4
	v_exp_f32_e32 v13, v13
	v_mul_f32_e32 v10, v10, v12
	v_mul_f32_e32 v12, v15, v18
	v_mul_f32_e32 v11, v11, v12
	v_cvt_pk_bf16_f32 v8, v8, v9
	v_cvt_pk_bf16_f32 v9, v10, v11
	v_add_f32_e32 v10, 1.0, v13
	v_rcp_f32_e32 v10, v10
	v_mul_f32_e32 v11, 0xbfb8aa3b, v5
	v_exp_f32_e32 v11, v11
	global_store_dwordx2 v[16:17], v[8:9], off
	v_mul_f32_e32 v4, v4, v10
	v_mul_f32_e32 v0, v0, v4
	v_add_f32_e32 v4, 1.0, v11
	v_mul_f32_e32 v8, 0xbfb8aa3b, v6
	v_rcp_f32_e32 v4, v4
	v_exp_f32_e32 v8, v8
	v_mul_f32_e32 v9, 0xbfb8aa3b, v7
	v_exp_f32_e32 v9, v9
	v_mul_f32_e32 v4, v5, v4
	v_add_f32_e32 v5, 1.0, v8
	v_rcp_f32_e32 v5, v5
	v_add_f32_e32 v8, 1.0, v9
	v_rcp_f32_e32 v8, v8
	v_mul_f32_e32 v1, v1, v4
	v_mul_f32_e32 v4, v6, v5
	v_mul_f32_e32 v2, v2, v4
	v_mul_f32_e32 v4, v7, v8
	v_mul_f32_e32 v3, v3, v4
	v_cvt_pk_bf16_f32 v0, v0, v1
	v_cvt_pk_bf16_f32 v1, v2, v3
	global_store_dwordx2 v[16:17], v[0:1], off offset:128
	s_branch .LBB0_179

.Lov_4:
	v_mul_f32_e32 v151, 0xbfb8aa3b, v124
	v_exp_f32_e32 v151, v151
	v_mul_f32_e32 v154, 0xbfb8aa3b, v125
	v_exp_f32_e32 v154, v154
	v_lshl_or_b32 v142, s69, 7, v146
	v_add_f32_e32 v151, 1.0, v151
	v_rcp_f32_e32 v151, v151
	v_lshl_add_u32 v150, s46, 8, v144
	v_ashrrev_i32_e32 v143, 31, v142
	v_mov_b64_e32 v[140:141], s[22:23]
	v_mul_f32_e32 v124, v124, v151
	v_mul_f32_e32 v120, v120, v124
	v_add_f32_e32 v124, 1.0, v154
	v_mul_f32_e32 v151, 0xbfb8aa3b, v126
	v_rcp_f32_e32 v124, v124
	v_exp_f32_e32 v151, v151
	v_mul_f32_e32 v154, 0xbfb8aa3b, v127
	v_exp_f32_e32 v154, v154
	v_mul_f32_e32 v124, v125, v124
	v_add_f32_e32 v125, 1.0, v151
	v_rcp_f32_e32 v125, v125
	v_add_f32_e32 v151, 1.0, v154
	v_rcp_f32_e32 v151, v151
	v_mul_f32_e32 v121, v121, v124
	v_mul_f32_e32 v124, v126, v125
	v_mul_f32_e32 v125, 0xbfb8aa3b, v116
	v_exp_f32_e32 v125, v125
	v_mul_f32_e32 v122, v122, v124
	v_mul_f32_e32 v124, v127, v151
	v_mul_f32_e32 v123, v123, v124
	v_cvt_pk_bf16_f32 v120, v120, v121
	v_cvt_pk_bf16_f32 v121, v122, v123
	v_add_f32_e32 v122, 1.0, v125
	v_rcp_f32_e32 v122, v122
	v_mul_f32_e32 v123, 0xbfb8aa3b, v117
	v_exp_f32_e32 v123, v123
	v_mad_i64_i32 v[152:153], s[48:49], v150, s68, v[140:141]
	v_lshlrev_b64 v[142:143], 1, v[142:143]
	v_lshl_add_u64 v[152:153], v[152:153], 0, v[142:143]
	v_mul_f32_e32 v116, v116, v122
	global_store_dwordx2 v[152:153], v[120:121], off
	v_mul_f32_e32 v112, v112, v116
	v_add_f32_e32 v116, 1.0, v123
	v_mul_f32_e32 v120, 0xbfb8aa3b, v118
	v_rcp_f32_e32 v116, v116
	v_exp_f32_e32 v120, v120
	v_mul_f32_e32 v121, 0xbfb8aa3b, v119
	v_exp_f32_e32 v121, v121
	v_mul_f32_e32 v116, v117, v116
	v_add_f32_e32 v117, 1.0, v120
	v_rcp_f32_e32 v117, v117
	v_add_f32_e32 v120, 1.0, v121
	v_rcp_f32_e32 v120, v120
	v_mul_f32_e32 v113, v113, v116
	v_mul_f32_e32 v116, v118, v117
	v_mul_f32_e32 v114, v114, v116
	v_mul_f32_e32 v116, v119, v120
	v_cvt_pk_bf16_f32 v112, v112, v113
	v_mul_f32_e32 v115, v115, v116
	v_cvt_pk_bf16_f32 v113, v114, v115
	global_store_dwordx2 v[152:153], v[112:113], off offset:128
	v_mul_f32_e32 v112, 0xbfb8aa3b, v108
	v_exp_f32_e32 v114, v112
	v_mul_f32_e32 v115, 0xbfb8aa3b, v109
	v_exp_f32_e32 v115, v115
	v_or_b32_e32 v112, 16, v150
	v_add_f32_e32 v114, 1.0, v114
	v_rcp_f32_e32 v114, v114
	v_mad_i64_i32 v[112:113], s[48:49], v112, s68, v[140:141]
	v_lshl_add_u64 v[112:113], v[112:113], 0, v[142:143]
	v_mul_f32_e32 v108, v108, v114
	v_mul_f32_e32 v104, v104, v108
	v_add_f32_e32 v108, 1.0, v115
	v_mul_f32_e32 v114, 0xbfb8aa3b, v110
	v_rcp_f32_e32 v108, v108
	v_exp_f32_e32 v114, v114
	v_mul_f32_e32 v115, 0xbfb8aa3b, v111
	v_exp_f32_e32 v115, v115
	v_mul_f32_e32 v108, v109, v108
	v_add_f32_e32 v109, 1.0, v114
	v_rcp_f32_e32 v109, v109
	v_add_f32_e32 v114, 1.0, v115
	v_rcp_f32_e32 v114, v114
	v_mul_f32_e32 v105, v105, v108
	v_mul_f32_e32 v108, v110, v109
	v_mul_f32_e32 v109, 0xbfb8aa3b, v100
	v_exp_f32_e32 v109, v109
	v_mul_f32_e32 v106, v106, v108
	v_mul_f32_e32 v108, v111, v114
	v_mul_f32_e32 v107, v107, v108
	v_cvt_pk_bf16_f32 v104, v104, v105
	v_cvt_pk_bf16_f32 v105, v106, v107
	v_add_f32_e32 v106, 1.0, v109
	v_rcp_f32_e32 v106, v106
	v_mul_f32_e32 v107, 0xbfb8aa3b, v101
	v_exp_f32_e32 v107, v107
	global_store_dwordx2 v[112:113], v[104:105], off
	v_mul_f32_e32 v100, v100, v106
	v_mul_f32_e32 v96, v96, v100
	v_add_f32_e32 v100, 1.0, v107
	v_mul_f32_e32 v104, 0xbfb8aa3b, v102
	v_rcp_f32_e32 v100, v100
	v_exp_f32_e32 v104, v104
	v_mul_f32_e32 v105, 0xbfb8aa3b, v103
	v_exp_f32_e32 v105, v105
	v_mul_f32_e32 v100, v101, v100
	v_add_f32_e32 v101, 1.0, v104
	v_rcp_f32_e32 v101, v101
	v_add_f32_e32 v104, 1.0, v105
	v_rcp_f32_e32 v104, v104
	v_mul_f32_e32 v97, v97, v100
	v_mul_f32_e32 v100, v102, v101
	v_mul_f32_e32 v98, v98, v100
	v_mul_f32_e32 v100, v103, v104
	v_cvt_pk_bf16_f32 v96, v96, v97
	v_mul_f32_e32 v99, v99, v100
	v_cvt_pk_bf16_f32 v97, v98, v99
	global_store_dwordx2 v[112:113], v[96:97], off offset:128
	v_mul_f32_e32 v96, 0xbfb8aa3b, v92
	v_exp_f32_e32 v98, v96
	v_mul_f32_e32 v99, 0xbfb8aa3b, v93
	v_exp_f32_e32 v99, v99
	v_or_b32_e32 v96, 32, v150
	v_add_f32_e32 v98, 1.0, v98
	v_rcp_f32_e32 v98, v98
	v_mad_i64_i32 v[96:97], s[48:49], v96, s68, v[140:141]
	v_lshl_add_u64 v[96:97], v[96:97], 0, v[142:143]
	v_mul_f32_e32 v92, v92, v98
	v_mul_f32_e32 v88, v88, v92
	v_add_f32_e32 v92, 1.0, v99
	v_mul_f32_e32 v98, 0xbfb8aa3b, v94
	v_rcp_f32_e32 v92, v92
	v_exp_f32_e32 v98, v98
	v_mul_f32_e32 v99, 0xbfb8aa3b, v95
	v_exp_f32_e32 v99, v99
	v_mul_f32_e32 v92, v93, v92
	v_add_f32_e32 v93, 1.0, v98
	v_rcp_f32_e32 v93, v93
	v_add_f32_e32 v98, 1.0, v99
	v_rcp_f32_e32 v98, v98
	v_mul_f32_e32 v89, v89, v92
	v_mul_f32_e32 v92, v94, v93
	v_mul_f32_e32 v93, 0xbfb8aa3b, v84
	v_exp_f32_e32 v93, v93
	v_mul_f32_e32 v90, v90, v92
	v_mul_f32_e32 v92, v95, v98
	v_mul_f32_e32 v91, v91, v92
	v_cvt_pk_bf16_f32 v88, v88, v89
	v_cvt_pk_bf16_f32 v89, v90, v91
	v_add_f32_e32 v90, 1.0, v93
	v_rcp_f32_e32 v90, v90
	v_mul_f32_e32 v91, 0xbfb8aa3b, v85
	v_exp_f32_e32 v91, v91
	global_store_dwordx2 v[96:97], v[88:89], off
	v_mul_f32_e32 v84, v84, v90
	v_mul_f32_e32 v80, v80, v84
	v_add_f32_e32 v84, 1.0, v91
	v_mul_f32_e32 v88, 0xbfb8aa3b, v86
	v_rcp_f32_e32 v84, v84
	v_exp_f32_e32 v88, v88
	v_mul_f32_e32 v89, 0xbfb8aa3b, v87
	v_exp_f32_e32 v89, v89
	v_mul_f32_e32 v84, v85, v84
	v_add_f32_e32 v85, 1.0, v88
	v_rcp_f32_e32 v85, v85
	v_add_f32_e32 v88, 1.0, v89
	v_rcp_f32_e32 v88, v88
	v_mul_f32_e32 v81, v81, v84
	v_mul_f32_e32 v84, v86, v85
	v_mul_f32_e32 v82, v82, v84
	v_mul_f32_e32 v84, v87, v88
	v_cvt_pk_bf16_f32 v80, v80, v81
	v_mul_f32_e32 v83, v83, v84
	v_cvt_pk_bf16_f32 v81, v82, v83
	global_store_dwordx2 v[96:97], v[80:81], off offset:128
	v_mul_f32_e32 v80, 0xbfb8aa3b, v76
	v_exp_f32_e32 v82, v80
	v_mul_f32_e32 v83, 0xbfb8aa3b, v77
	v_exp_f32_e32 v83, v83
	v_or_b32_e32 v80, 48, v150
	v_add_f32_e32 v82, 1.0, v82
	v_rcp_f32_e32 v82, v82
	v_mad_i64_i32 v[80:81], s[48:49], v80, s68, v[140:141]
	v_lshl_add_u64 v[80:81], v[80:81], 0, v[142:143]
	v_mul_f32_e32 v76, v76, v82
	v_mul_f32_e32 v72, v72, v76
	v_add_f32_e32 v76, 1.0, v83
	v_mul_f32_e32 v82, 0xbfb8aa3b, v78
	v_rcp_f32_e32 v76, v76
	v_exp_f32_e32 v82, v82
	v_mul_f32_e32 v83, 0xbfb8aa3b, v79
	v_exp_f32_e32 v83, v83
	v_mul_f32_e32 v76, v77, v76
	v_add_f32_e32 v77, 1.0, v82
	v_rcp_f32_e32 v77, v77
	v_add_f32_e32 v82, 1.0, v83
	v_rcp_f32_e32 v82, v82
	v_mul_f32_e32 v73, v73, v76
	v_mul_f32_e32 v76, v78, v77
	v_mul_f32_e32 v77, 0xbfb8aa3b, v68
	v_exp_f32_e32 v77, v77
	v_mul_f32_e32 v74, v74, v76
	v_mul_f32_e32 v76, v79, v82
	v_mul_f32_e32 v75, v75, v76
	v_cvt_pk_bf16_f32 v72, v72, v73
	v_cvt_pk_bf16_f32 v73, v74, v75
	v_add_f32_e32 v74, 1.0, v77
	v_rcp_f32_e32 v74, v74
	v_mul_f32_e32 v75, 0xbfb8aa3b, v69
	v_exp_f32_e32 v75, v75
	global_store_dwordx2 v[80:81], v[72:73], off
	v_mul_f32_e32 v68, v68, v74
	v_mul_f32_e32 v64, v64, v68
	v_add_f32_e32 v68, 1.0, v75
	v_mul_f32_e32 v72, 0xbfb8aa3b, v70
	v_rcp_f32_e32 v68, v68
	v_exp_f32_e32 v72, v72
	v_mul_f32_e32 v73, 0xbfb8aa3b, v71
	v_exp_f32_e32 v73, v73
	v_mul_f32_e32 v68, v69, v68
	v_add_f32_e32 v69, 1.0, v72
	v_rcp_f32_e32 v69, v69
	v_add_f32_e32 v72, 1.0, v73
	v_rcp_f32_e32 v72, v72
	v_mul_f32_e32 v65, v65, v68
	v_mul_f32_e32 v68, v70, v69
	v_mul_f32_e32 v66, v66, v68
	v_mul_f32_e32 v68, v71, v72
	v_cvt_pk_bf16_f32 v64, v64, v65
	v_mul_f32_e32 v67, v67, v68
	v_cvt_pk_bf16_f32 v65, v66, v67
	global_store_dwordx2 v[80:81], v[64:65], off offset:128
	v_mov_b32_e32 v216, v140
	v_mov_b32_e32 v217, v141
	v_mov_b32_e32 v218, v142
	v_mov_b32_e32 v219, v143
	v_mov_b32_e32 v220, v150
	s_andn2_b64 vcc, exec, s[0:1]
	s_cbranch_vccnz .Lov_nb_4
	s_barrier
	v_mul_f32_e32 v64, 0xbfb8aa3b, v60
	v_exp_f32_e32 v66, v64
	v_mul_f32_e32 v67, 0xbfb8aa3b, v61
	v_exp_f32_e32 v67, v67
	v_add_u32_e32 v64, 0x80, v150
	v_add_f32_e32 v66, 1.0, v66
	v_rcp_f32_e32 v66, v66
	v_mad_i64_i32 v[64:65], vcc, v64, s68, v[140:141]
	v_lshl_add_u64 v[64:65], v[64:65], 0, v[142:143]
	v_mul_f32_e32 v60, v60, v66
	v_mul_f32_e32 v56, v56, v60
	v_add_f32_e32 v60, 1.0, v67
	v_mul_f32_e32 v66, 0xbfb8aa3b, v62
	v_rcp_f32_e32 v60, v60
	v_exp_f32_e32 v66, v66
	v_mul_f32_e32 v67, 0xbfb8aa3b, v63
	v_exp_f32_e32 v67, v67
	v_mul_f32_e32 v60, v61, v60
	v_add_f32_e32 v61, 1.0, v66
	v_rcp_f32_e32 v61, v61
	v_add_f32_e32 v66, 1.0, v67
	v_rcp_f32_e32 v66, v66
	v_mul_f32_e32 v57, v57, v60
	v_mul_f32_e32 v60, v62, v61
	v_mul_f32_e32 v61, 0xbfb8aa3b, v52
	v_exp_f32_e32 v61, v61
	v_mul_f32_e32 v58, v58, v60
	v_mul_f32_e32 v60, v63, v66
	v_mul_f32_e32 v59, v59, v60
	v_cvt_pk_bf16_f32 v56, v56, v57
	v_cvt_pk_bf16_f32 v57, v58, v59
	v_add_f32_e32 v58, 1.0, v61
	v_rcp_f32_e32 v58, v58
	v_mul_f32_e32 v59, 0xbfb8aa3b, v53
	v_exp_f32_e32 v59, v59
	global_store_dwordx2 v[64:65], v[56:57], off
	v_mul_f32_e32 v52, v52, v58
	v_mul_f32_e32 v48, v48, v52
	v_add_f32_e32 v52, 1.0, v59
	v_mul_f32_e32 v56, 0xbfb8aa3b, v54
	v_rcp_f32_e32 v52, v52
	v_exp_f32_e32 v56, v56
	v_mul_f32_e32 v57, 0xbfb8aa3b, v55
	v_exp_f32_e32 v57, v57
	v_mul_f32_e32 v52, v53, v52
	v_add_f32_e32 v53, 1.0, v56
	v_rcp_f32_e32 v53, v53
	v_add_f32_e32 v56, 1.0, v57
	v_rcp_f32_e32 v56, v56
	v_mul_f32_e32 v49, v49, v52
	v_mul_f32_e32 v52, v54, v53
	v_mul_f32_e32 v50, v50, v52
	v_mul_f32_e32 v52, v55, v56
	v_cvt_pk_bf16_f32 v48, v48, v49
	v_mul_f32_e32 v51, v51, v52
	v_cvt_pk_bf16_f32 v49, v50, v51
	global_store_dwordx2 v[64:65], v[48:49], off offset:128
	v_mul_f32_e32 v48, 0xbfb8aa3b, v44
	v_exp_f32_e32 v50, v48
	v_mul_f32_e32 v51, 0xbfb8aa3b, v45
	v_exp_f32_e32 v51, v51
	v_add_u32_e32 v48, 0x90, v150
	v_add_f32_e32 v50, 1.0, v50
	v_rcp_f32_e32 v50, v50
	v_mad_i64_i32 v[48:49], vcc, v48, s68, v[140:141]
	v_lshl_add_u64 v[48:49], v[48:49], 0, v[142:143]
	v_mul_f32_e32 v44, v44, v50
	v_mul_f32_e32 v40, v40, v44
	v_add_f32_e32 v44, 1.0, v51
	v_mul_f32_e32 v50, 0xbfb8aa3b, v46
	v_rcp_f32_e32 v44, v44
	v_exp_f32_e32 v50, v50
	v_mul_f32_e32 v51, 0xbfb8aa3b, v47
	v_exp_f32_e32 v51, v51
	v_mul_f32_e32 v44, v45, v44
	v_add_f32_e32 v45, 1.0, v50
	v_rcp_f32_e32 v45, v45
	v_add_f32_e32 v50, 1.0, v51
	v_rcp_f32_e32 v50, v50
	v_mul_f32_e32 v41, v41, v44
	v_mul_f32_e32 v44, v46, v45
	v_mul_f32_e32 v45, 0xbfb8aa3b, v36
	v_exp_f32_e32 v45, v45
	v_mul_f32_e32 v42, v42, v44
	v_mul_f32_e32 v44, v47, v50
	v_mul_f32_e32 v43, v43, v44
	v_cvt_pk_bf16_f32 v40, v40, v41
	v_cvt_pk_bf16_f32 v41, v42, v43
	v_add_f32_e32 v42, 1.0, v45
	v_rcp_f32_e32 v42, v42
	v_mul_f32_e32 v43, 0xbfb8aa3b, v37
	v_exp_f32_e32 v43, v43
	global_store_dwordx2 v[48:49], v[40:41], off
	v_mul_f32_e32 v36, v36, v42
	v_mul_f32_e32 v32, v32, v36
	v_add_f32_e32 v36, 1.0, v43
	v_mul_f32_e32 v40, 0xbfb8aa3b, v38
	v_rcp_f32_e32 v36, v36
	v_exp_f32_e32 v40, v40
	v_mul_f32_e32 v41, 0xbfb8aa3b, v39
	v_exp_f32_e32 v41, v41
	v_mul_f32_e32 v36, v37, v36
	v_add_f32_e32 v37, 1.0, v40
	v_rcp_f32_e32 v37, v37
	v_add_f32_e32 v40, 1.0, v41
	v_rcp_f32_e32 v40, v40
	v_mul_f32_e32 v33, v33, v36
	v_mul_f32_e32 v36, v38, v37
	v_mul_f32_e32 v34, v34, v36
	v_mul_f32_e32 v36, v39, v40
	v_cvt_pk_bf16_f32 v32, v32, v33
	v_mul_f32_e32 v35, v35, v36
	v_cvt_pk_bf16_f32 v33, v34, v35
	global_store_dwordx2 v[48:49], v[32:33], off offset:128
	v_mul_f32_e32 v32, 0xbfb8aa3b, v28
	v_exp_f32_e32 v34, v32
	v_mul_f32_e32 v35, 0xbfb8aa3b, v29
	v_exp_f32_e32 v35, v35
	v_add_u32_e32 v32, 0xa0, v150
	v_add_f32_e32 v34, 1.0, v34
	v_rcp_f32_e32 v34, v34
	v_mad_i64_i32 v[32:33], vcc, v32, s68, v[140:141]
	v_lshl_add_u64 v[32:33], v[32:33], 0, v[142:143]
	v_mul_f32_e32 v28, v28, v34
	v_mul_f32_e32 v24, v24, v28
	v_add_f32_e32 v28, 1.0, v35
	v_mul_f32_e32 v34, 0xbfb8aa3b, v30
	v_rcp_f32_e32 v28, v28
	v_exp_f32_e32 v34, v34
	v_mul_f32_e32 v35, 0xbfb8aa3b, v31
	v_exp_f32_e32 v35, v35
	v_mul_f32_e32 v28, v29, v28
	v_add_f32_e32 v29, 1.0, v34
	v_rcp_f32_e32 v29, v29
	v_add_f32_e32 v34, 1.0, v35
	v_rcp_f32_e32 v34, v34
	v_mul_f32_e32 v25, v25, v28
	v_mul_f32_e32 v28, v30, v29
	v_mul_f32_e32 v29, 0xbfb8aa3b, v20
	v_exp_f32_e32 v29, v29
	v_mul_f32_e32 v26, v26, v28
	v_mul_f32_e32 v28, v31, v34
	v_mul_f32_e32 v27, v27, v28
	v_cvt_pk_bf16_f32 v24, v24, v25
	v_cvt_pk_bf16_f32 v25, v26, v27
	v_add_f32_e32 v26, 1.0, v29
	v_rcp_f32_e32 v26, v26
	v_mul_f32_e32 v27, 0xbfb8aa3b, v21
	v_exp_f32_e32 v27, v27
	global_store_dwordx2 v[32:33], v[24:25], off
	v_mul_f32_e32 v20, v20, v26
	v_mul_f32_e32 v16, v16, v20
	v_add_f32_e32 v20, 1.0, v27
	v_mul_f32_e32 v24, 0xbfb8aa3b, v22
	v_rcp_f32_e32 v20, v20
	v_exp_f32_e32 v24, v24
	v_mul_f32_e32 v25, 0xbfb8aa3b, v23
	v_exp_f32_e32 v25, v25
	v_mul_f32_e32 v20, v21, v20
	v_add_f32_e32 v21, 1.0, v24
	v_rcp_f32_e32 v21, v21
	v_add_f32_e32 v24, 1.0, v25
	v_rcp_f32_e32 v24, v24
	v_mul_f32_e32 v17, v17, v20
	v_mul_f32_e32 v20, v22, v21
	v_mul_f32_e32 v18, v18, v20
	v_mul_f32_e32 v20, v23, v24
	v_cvt_pk_bf16_f32 v16, v16, v17
	v_mul_f32_e32 v19, v19, v20
	v_cvt_pk_bf16_f32 v17, v18, v19
	global_store_dwordx2 v[32:33], v[16:17], off offset:128
	v_mul_f32_e32 v16, 0xbfb8aa3b, v12
	v_exp_f32_e32 v18, v16
	v_mul_f32_e32 v19, 0xbfb8aa3b, v13
	v_exp_f32_e32 v19, v19
	v_add_u32_e32 v16, 0xb0, v150
	v_add_f32_e32 v18, 1.0, v18
	v_rcp_f32_e32 v18, v18
	v_mad_i64_i32 v[16:17], vcc, v16, s68, v[140:141]
	v_lshl_add_u64 v[16:17], v[16:17], 0, v[142:143]
	v_mul_f32_e32 v12, v12, v18
	v_mul_f32_e32 v8, v8, v12
	v_add_f32_e32 v12, 1.0, v19
	v_mul_f32_e32 v18, 0xbfb8aa3b, v14
	v_rcp_f32_e32 v12, v12
	v_exp_f32_e32 v18, v18
	v_mul_f32_e32 v19, 0xbfb8aa3b, v15
	v_exp_f32_e32 v19, v19
	v_mul_f32_e32 v12, v13, v12
	v_add_f32_e32 v13, 1.0, v18
	v_rcp_f32_e32 v13, v13
	v_add_f32_e32 v18, 1.0, v19
	v_rcp_f32_e32 v18, v18
	v_mul_f32_e32 v9, v9, v12
	v_mul_f32_e32 v12, v14, v13
	v_mul_f32_e32 v13, 0xbfb8aa3b, v4
	v_exp_f32_e32 v13, v13
	v_mul_f32_e32 v10, v10, v12
	v_mul_f32_e32 v12, v15, v18
	v_mul_f32_e32 v11, v11, v12
	v_cvt_pk_bf16_f32 v8, v8, v9
	v_cvt_pk_bf16_f32 v9, v10, v11
	v_add_f32_e32 v10, 1.0, v13
	v_rcp_f32_e32 v10, v10
	v_mul_f32_e32 v11, 0xbfb8aa3b, v5
	v_exp_f32_e32 v11, v11
	global_store_dwordx2 v[16:17], v[8:9], off
	v_mul_f32_e32 v4, v4, v10
	v_mul_f32_e32 v0, v0, v4
	v_add_f32_e32 v4, 1.0, v11
	v_mul_f32_e32 v8, 0xbfb8aa3b, v6
	v_rcp_f32_e32 v4, v4
	v_exp_f32_e32 v8, v8
	v_mul_f32_e32 v9, 0xbfb8aa3b, v7
	v_exp_f32_e32 v9, v9
	v_mul_f32_e32 v4, v5, v4
	v_add_f32_e32 v5, 1.0, v8
	v_rcp_f32_e32 v5, v5
	v_add_f32_e32 v8, 1.0, v9
	v_rcp_f32_e32 v8, v8
	v_mul_f32_e32 v1, v1, v4
	v_mul_f32_e32 v4, v6, v5
	v_mul_f32_e32 v2, v2, v4
	v_mul_f32_e32 v4, v7, v8
	v_mul_f32_e32 v3, v3, v4
	v_cvt_pk_bf16_f32 v0, v0, v1
	v_cvt_pk_bf16_f32 v1, v2, v3
	global_store_dwordx2 v[16:17], v[0:1], off offset:128
	s_branch .LBB0_719

.Lov_7:
	v_mul_f32_e32 v151, 0xbfb8aa3b, v124
	v_exp_f32_e32 v151, v151
	v_mul_f32_e32 v154, 0xbfb8aa3b, v125
	v_exp_f32_e32 v154, v154
	v_lshl_or_b32 v142, s71, 7, v146
	v_add_f32_e32 v151, 1.0, v151
	v_rcp_f32_e32 v151, v151
	v_lshl_add_u32 v150, s48, 8, v144
	v_ashrrev_i32_e32 v143, 31, v142
	v_mov_b64_e32 v[140:141], s[22:23]
	v_mul_f32_e32 v124, v124, v151
	v_mul_f32_e32 v120, v120, v124
	v_add_f32_e32 v124, 1.0, v154
	v_mul_f32_e32 v151, 0xbfb8aa3b, v126
	v_rcp_f32_e32 v124, v124
	v_exp_f32_e32 v151, v151
	v_mul_f32_e32 v154, 0xbfb8aa3b, v127
	v_exp_f32_e32 v154, v154
	v_mul_f32_e32 v124, v125, v124
	v_add_f32_e32 v125, 1.0, v151
	v_rcp_f32_e32 v125, v125
	v_add_f32_e32 v151, 1.0, v154
	v_rcp_f32_e32 v151, v151
	v_mul_f32_e32 v121, v121, v124
	v_mul_f32_e32 v124, v126, v125
	v_mul_f32_e32 v125, 0xbfb8aa3b, v116
	v_exp_f32_e32 v125, v125
	v_mul_f32_e32 v122, v122, v124
	v_mul_f32_e32 v124, v127, v151
	v_mul_f32_e32 v123, v123, v124
	v_cvt_pk_bf16_f32 v120, v120, v121
	v_cvt_pk_bf16_f32 v121, v122, v123
	v_add_f32_e32 v122, 1.0, v125
	v_rcp_f32_e32 v122, v122
	v_mul_f32_e32 v123, 0xbfb8aa3b, v117
	v_exp_f32_e32 v123, v123
	v_mad_i64_i32 v[152:153], s[52:53], v150, s70, v[140:141]
	v_lshlrev_b64 v[142:143], 1, v[142:143]
	v_lshl_add_u64 v[152:153], v[152:153], 0, v[142:143]
	v_mul_f32_e32 v116, v116, v122
	global_store_dwordx2 v[152:153], v[120:121], off
	v_mul_f32_e32 v112, v112, v116
	v_add_f32_e32 v116, 1.0, v123
	v_mul_f32_e32 v120, 0xbfb8aa3b, v118
	v_rcp_f32_e32 v116, v116
	v_exp_f32_e32 v120, v120
	v_mul_f32_e32 v121, 0xbfb8aa3b, v119
	v_exp_f32_e32 v121, v121
	v_mul_f32_e32 v116, v117, v116
	v_add_f32_e32 v117, 1.0, v120
	v_rcp_f32_e32 v117, v117
	v_add_f32_e32 v120, 1.0, v121
	v_rcp_f32_e32 v120, v120
	v_mul_f32_e32 v113, v113, v116
	v_mul_f32_e32 v116, v118, v117
	v_mul_f32_e32 v114, v114, v116
	v_mul_f32_e32 v116, v119, v120
	v_cvt_pk_bf16_f32 v112, v112, v113
	v_mul_f32_e32 v115, v115, v116
	v_cvt_pk_bf16_f32 v113, v114, v115
	global_store_dwordx2 v[152:153], v[112:113], off offset:128
	v_mul_f32_e32 v112, 0xbfb8aa3b, v108
	v_exp_f32_e32 v114, v112
	v_mul_f32_e32 v115, 0xbfb8aa3b, v109
	v_exp_f32_e32 v115, v115
	v_or_b32_e32 v112, 16, v150
	v_add_f32_e32 v114, 1.0, v114
	v_rcp_f32_e32 v114, v114
	v_mad_i64_i32 v[112:113], s[52:53], v112, s70, v[140:141]
	v_lshl_add_u64 v[112:113], v[112:113], 0, v[142:143]
	v_mul_f32_e32 v108, v108, v114
	v_mul_f32_e32 v104, v104, v108
	v_add_f32_e32 v108, 1.0, v115
	v_mul_f32_e32 v114, 0xbfb8aa3b, v110
	v_rcp_f32_e32 v108, v108
	v_exp_f32_e32 v114, v114
	v_mul_f32_e32 v115, 0xbfb8aa3b, v111
	v_exp_f32_e32 v115, v115
	v_mul_f32_e32 v108, v109, v108
	v_add_f32_e32 v109, 1.0, v114
	v_rcp_f32_e32 v109, v109
	v_add_f32_e32 v114, 1.0, v115
	v_rcp_f32_e32 v114, v114
	v_mul_f32_e32 v105, v105, v108
	v_mul_f32_e32 v108, v110, v109
	v_mul_f32_e32 v109, 0xbfb8aa3b, v100
	v_exp_f32_e32 v109, v109
	v_mul_f32_e32 v106, v106, v108
	v_mul_f32_e32 v108, v111, v114
	v_mul_f32_e32 v107, v107, v108
	v_cvt_pk_bf16_f32 v104, v104, v105
	v_cvt_pk_bf16_f32 v105, v106, v107
	v_add_f32_e32 v106, 1.0, v109
	v_rcp_f32_e32 v106, v106
	v_mul_f32_e32 v107, 0xbfb8aa3b, v101
	v_exp_f32_e32 v107, v107
	global_store_dwordx2 v[112:113], v[104:105], off
	v_mul_f32_e32 v100, v100, v106
	v_mul_f32_e32 v96, v96, v100
	v_add_f32_e32 v100, 1.0, v107
	v_mul_f32_e32 v104, 0xbfb8aa3b, v102
	v_rcp_f32_e32 v100, v100
	v_exp_f32_e32 v104, v104
	v_mul_f32_e32 v105, 0xbfb8aa3b, v103
	v_exp_f32_e32 v105, v105
	v_mul_f32_e32 v100, v101, v100
	v_add_f32_e32 v101, 1.0, v104
	v_rcp_f32_e32 v101, v101
	v_add_f32_e32 v104, 1.0, v105
	v_rcp_f32_e32 v104, v104
	v_mul_f32_e32 v97, v97, v100
	v_mul_f32_e32 v100, v102, v101
	v_mul_f32_e32 v98, v98, v100
	v_mul_f32_e32 v100, v103, v104
	v_cvt_pk_bf16_f32 v96, v96, v97
	v_mul_f32_e32 v99, v99, v100
	v_cvt_pk_bf16_f32 v97, v98, v99
	global_store_dwordx2 v[112:113], v[96:97], off offset:128
	v_mul_f32_e32 v96, 0xbfb8aa3b, v92
	v_exp_f32_e32 v98, v96
	v_mul_f32_e32 v99, 0xbfb8aa3b, v93
	v_exp_f32_e32 v99, v99
	v_or_b32_e32 v96, 32, v150
	v_add_f32_e32 v98, 1.0, v98
	v_rcp_f32_e32 v98, v98
	v_mad_i64_i32 v[96:97], s[52:53], v96, s70, v[140:141]
	v_lshl_add_u64 v[96:97], v[96:97], 0, v[142:143]
	v_mul_f32_e32 v92, v92, v98
	v_mul_f32_e32 v88, v88, v92
	v_add_f32_e32 v92, 1.0, v99
	v_mul_f32_e32 v98, 0xbfb8aa3b, v94
	v_rcp_f32_e32 v92, v92
	v_exp_f32_e32 v98, v98
	v_mul_f32_e32 v99, 0xbfb8aa3b, v95
	v_exp_f32_e32 v99, v99
	v_mul_f32_e32 v92, v93, v92
	v_add_f32_e32 v93, 1.0, v98
	v_rcp_f32_e32 v93, v93
	v_add_f32_e32 v98, 1.0, v99
	v_rcp_f32_e32 v98, v98
	v_mul_f32_e32 v89, v89, v92
	v_mul_f32_e32 v92, v94, v93
	v_mul_f32_e32 v93, 0xbfb8aa3b, v84
	v_exp_f32_e32 v93, v93
	v_mul_f32_e32 v90, v90, v92
	v_mul_f32_e32 v92, v95, v98
	v_mul_f32_e32 v91, v91, v92
	v_cvt_pk_bf16_f32 v88, v88, v89
	v_cvt_pk_bf16_f32 v89, v90, v91
	v_add_f32_e32 v90, 1.0, v93
	v_rcp_f32_e32 v90, v90
	v_mul_f32_e32 v91, 0xbfb8aa3b, v85
	v_exp_f32_e32 v91, v91
	global_store_dwordx2 v[96:97], v[88:89], off
	v_mul_f32_e32 v84, v84, v90
	v_mul_f32_e32 v80, v80, v84
	v_add_f32_e32 v84, 1.0, v91
	v_mul_f32_e32 v88, 0xbfb8aa3b, v86
	v_rcp_f32_e32 v84, v84
	v_exp_f32_e32 v88, v88
	v_mul_f32_e32 v89, 0xbfb8aa3b, v87
	v_exp_f32_e32 v89, v89
	v_mul_f32_e32 v84, v85, v84
	v_add_f32_e32 v85, 1.0, v88
	v_rcp_f32_e32 v85, v85
	v_add_f32_e32 v88, 1.0, v89
	v_rcp_f32_e32 v88, v88
	v_mul_f32_e32 v81, v81, v84
	v_mul_f32_e32 v84, v86, v85
	v_mul_f32_e32 v82, v82, v84
	v_mul_f32_e32 v84, v87, v88
	v_cvt_pk_bf16_f32 v80, v80, v81
	v_mul_f32_e32 v83, v83, v84
	v_cvt_pk_bf16_f32 v81, v82, v83
	global_store_dwordx2 v[96:97], v[80:81], off offset:128
	v_mul_f32_e32 v80, 0xbfb8aa3b, v76
	v_exp_f32_e32 v82, v80
	v_mul_f32_e32 v83, 0xbfb8aa3b, v77
	v_exp_f32_e32 v83, v83
	v_or_b32_e32 v80, 48, v150
	v_add_f32_e32 v82, 1.0, v82
	v_rcp_f32_e32 v82, v82
	v_mad_i64_i32 v[80:81], s[52:53], v80, s70, v[140:141]
	v_lshl_add_u64 v[80:81], v[80:81], 0, v[142:143]
	v_mul_f32_e32 v76, v76, v82
	v_mul_f32_e32 v72, v72, v76
	v_add_f32_e32 v76, 1.0, v83
	v_mul_f32_e32 v82, 0xbfb8aa3b, v78
	v_rcp_f32_e32 v76, v76
	v_exp_f32_e32 v82, v82
	v_mul_f32_e32 v83, 0xbfb8aa3b, v79
	v_exp_f32_e32 v83, v83
	v_mul_f32_e32 v76, v77, v76
	v_add_f32_e32 v77, 1.0, v82
	v_rcp_f32_e32 v77, v77
	v_add_f32_e32 v82, 1.0, v83
	v_rcp_f32_e32 v82, v82
	v_mul_f32_e32 v73, v73, v76
	v_mul_f32_e32 v76, v78, v77
	v_mul_f32_e32 v77, 0xbfb8aa3b, v68
	v_exp_f32_e32 v77, v77
	v_mul_f32_e32 v74, v74, v76
	v_mul_f32_e32 v76, v79, v82
	v_mul_f32_e32 v75, v75, v76
	v_cvt_pk_bf16_f32 v72, v72, v73
	v_cvt_pk_bf16_f32 v73, v74, v75
	v_add_f32_e32 v74, 1.0, v77
	v_rcp_f32_e32 v74, v74
	v_mul_f32_e32 v75, 0xbfb8aa3b, v69
	v_exp_f32_e32 v75, v75
	global_store_dwordx2 v[80:81], v[72:73], off
	v_mul_f32_e32 v68, v68, v74
	v_mul_f32_e32 v64, v64, v68
	v_add_f32_e32 v68, 1.0, v75
	v_mul_f32_e32 v72, 0xbfb8aa3b, v70
	v_rcp_f32_e32 v68, v68
	v_exp_f32_e32 v72, v72
	v_mul_f32_e32 v73, 0xbfb8aa3b, v71
	v_exp_f32_e32 v73, v73
	v_mul_f32_e32 v68, v69, v68
	v_add_f32_e32 v69, 1.0, v72
	v_rcp_f32_e32 v69, v69
	v_add_f32_e32 v72, 1.0, v73
	v_rcp_f32_e32 v72, v72
	v_mul_f32_e32 v65, v65, v68
	v_mul_f32_e32 v68, v70, v69
	v_mul_f32_e32 v66, v66, v68
	v_mul_f32_e32 v68, v71, v72
	v_cvt_pk_bf16_f32 v64, v64, v65
	v_mul_f32_e32 v67, v67, v68
	v_cvt_pk_bf16_f32 v65, v66, v67
	global_store_dwordx2 v[80:81], v[64:65], off offset:128
	v_mov_b32_e32 v216, v140
	v_mov_b32_e32 v217, v141
	v_mov_b32_e32 v218, v142
	v_mov_b32_e32 v219, v143
	v_mov_b32_e32 v220, v150
	s_andn2_b64 vcc, exec, s[0:1]
	s_cbranch_vccnz .Lov_nb_7
	s_barrier
	v_mul_f32_e32 v64, 0xbfb8aa3b, v60
	v_exp_f32_e32 v66, v64
	v_mul_f32_e32 v67, 0xbfb8aa3b, v61
	v_exp_f32_e32 v67, v67
	v_add_u32_e32 v64, 0x80, v150
	v_add_f32_e32 v66, 1.0, v66
	v_rcp_f32_e32 v66, v66
	v_mad_i64_i32 v[64:65], vcc, v64, s70, v[140:141]
	v_lshl_add_u64 v[64:65], v[64:65], 0, v[142:143]
	v_mul_f32_e32 v60, v60, v66
	v_mul_f32_e32 v56, v56, v60
	v_add_f32_e32 v60, 1.0, v67
	v_mul_f32_e32 v66, 0xbfb8aa3b, v62
	v_rcp_f32_e32 v60, v60
	v_exp_f32_e32 v66, v66
	v_mul_f32_e32 v67, 0xbfb8aa3b, v63
	v_exp_f32_e32 v67, v67
	v_mul_f32_e32 v60, v61, v60
	v_add_f32_e32 v61, 1.0, v66
	v_rcp_f32_e32 v61, v61
	v_add_f32_e32 v66, 1.0, v67
	v_rcp_f32_e32 v66, v66
	v_mul_f32_e32 v57, v57, v60
	v_mul_f32_e32 v60, v62, v61
	v_mul_f32_e32 v61, 0xbfb8aa3b, v52
	v_exp_f32_e32 v61, v61
	v_mul_f32_e32 v58, v58, v60
	v_mul_f32_e32 v60, v63, v66
	v_mul_f32_e32 v59, v59, v60
	v_cvt_pk_bf16_f32 v56, v56, v57
	v_cvt_pk_bf16_f32 v57, v58, v59
	v_add_f32_e32 v58, 1.0, v61
	v_rcp_f32_e32 v58, v58
	v_mul_f32_e32 v59, 0xbfb8aa3b, v53
	v_exp_f32_e32 v59, v59
	global_store_dwordx2 v[64:65], v[56:57], off
	v_mul_f32_e32 v52, v52, v58
	v_mul_f32_e32 v48, v48, v52
	v_add_f32_e32 v52, 1.0, v59
	v_mul_f32_e32 v56, 0xbfb8aa3b, v54
	v_rcp_f32_e32 v52, v52
	v_exp_f32_e32 v56, v56
	v_mul_f32_e32 v57, 0xbfb8aa3b, v55
	v_exp_f32_e32 v57, v57
	v_mul_f32_e32 v52, v53, v52
	v_add_f32_e32 v53, 1.0, v56
	v_rcp_f32_e32 v53, v53
	v_add_f32_e32 v56, 1.0, v57
	v_rcp_f32_e32 v56, v56
	v_mul_f32_e32 v49, v49, v52
	v_mul_f32_e32 v52, v54, v53
	v_mul_f32_e32 v50, v50, v52
	v_mul_f32_e32 v52, v55, v56
	v_cvt_pk_bf16_f32 v48, v48, v49
	v_mul_f32_e32 v51, v51, v52
	v_cvt_pk_bf16_f32 v49, v50, v51
	global_store_dwordx2 v[64:65], v[48:49], off offset:128
	v_mul_f32_e32 v48, 0xbfb8aa3b, v44
	v_exp_f32_e32 v50, v48
	v_mul_f32_e32 v51, 0xbfb8aa3b, v45
	v_exp_f32_e32 v51, v51
	v_add_u32_e32 v48, 0x90, v150
	v_add_f32_e32 v50, 1.0, v50
	v_rcp_f32_e32 v50, v50
	v_mad_i64_i32 v[48:49], vcc, v48, s70, v[140:141]
	v_lshl_add_u64 v[48:49], v[48:49], 0, v[142:143]
	v_mul_f32_e32 v44, v44, v50
	v_mul_f32_e32 v40, v40, v44
	v_add_f32_e32 v44, 1.0, v51
	v_mul_f32_e32 v50, 0xbfb8aa3b, v46
	v_rcp_f32_e32 v44, v44
	v_exp_f32_e32 v50, v50
	v_mul_f32_e32 v51, 0xbfb8aa3b, v47
	v_exp_f32_e32 v51, v51
	v_mul_f32_e32 v44, v45, v44
	v_add_f32_e32 v45, 1.0, v50
	v_rcp_f32_e32 v45, v45
	v_add_f32_e32 v50, 1.0, v51
	v_rcp_f32_e32 v50, v50
	v_mul_f32_e32 v41, v41, v44
	v_mul_f32_e32 v44, v46, v45
	v_mul_f32_e32 v45, 0xbfb8aa3b, v36
	v_exp_f32_e32 v45, v45
	v_mul_f32_e32 v42, v42, v44
	v_mul_f32_e32 v44, v47, v50
	v_mul_f32_e32 v43, v43, v44
	v_cvt_pk_bf16_f32 v40, v40, v41
	v_cvt_pk_bf16_f32 v41, v42, v43
	v_add_f32_e32 v42, 1.0, v45
	v_rcp_f32_e32 v42, v42
	v_mul_f32_e32 v43, 0xbfb8aa3b, v37
	v_exp_f32_e32 v43, v43
	global_store_dwordx2 v[48:49], v[40:41], off
	v_mul_f32_e32 v36, v36, v42
	v_mul_f32_e32 v32, v32, v36
	v_add_f32_e32 v36, 1.0, v43
	v_mul_f32_e32 v40, 0xbfb8aa3b, v38
	v_rcp_f32_e32 v36, v36
	v_exp_f32_e32 v40, v40
	v_mul_f32_e32 v41, 0xbfb8aa3b, v39
	v_exp_f32_e32 v41, v41
	v_mul_f32_e32 v36, v37, v36
	v_add_f32_e32 v37, 1.0, v40
	v_rcp_f32_e32 v37, v37
	v_add_f32_e32 v40, 1.0, v41
	v_rcp_f32_e32 v40, v40
	v_mul_f32_e32 v33, v33, v36
	v_mul_f32_e32 v36, v38, v37
	v_mul_f32_e32 v34, v34, v36
	v_mul_f32_e32 v36, v39, v40
	v_cvt_pk_bf16_f32 v32, v32, v33
	v_mul_f32_e32 v35, v35, v36
	v_cvt_pk_bf16_f32 v33, v34, v35
	global_store_dwordx2 v[48:49], v[32:33], off offset:128
	v_mul_f32_e32 v32, 0xbfb8aa3b, v28
	v_exp_f32_e32 v34, v32
	v_mul_f32_e32 v35, 0xbfb8aa3b, v29
	v_exp_f32_e32 v35, v35
	v_add_u32_e32 v32, 0xa0, v150
	v_add_f32_e32 v34, 1.0, v34
	v_rcp_f32_e32 v34, v34
	v_mad_i64_i32 v[32:33], vcc, v32, s70, v[140:141]
	v_lshl_add_u64 v[32:33], v[32:33], 0, v[142:143]
	v_mul_f32_e32 v28, v28, v34
	v_mul_f32_e32 v24, v24, v28
	v_add_f32_e32 v28, 1.0, v35
	v_mul_f32_e32 v34, 0xbfb8aa3b, v30
	v_rcp_f32_e32 v28, v28
	v_exp_f32_e32 v34, v34
	v_mul_f32_e32 v35, 0xbfb8aa3b, v31
	v_exp_f32_e32 v35, v35
	v_mul_f32_e32 v28, v29, v28
	v_add_f32_e32 v29, 1.0, v34
	v_rcp_f32_e32 v29, v29
	v_add_f32_e32 v34, 1.0, v35
	v_rcp_f32_e32 v34, v34
	v_mul_f32_e32 v25, v25, v28
	v_mul_f32_e32 v28, v30, v29
	v_mul_f32_e32 v29, 0xbfb8aa3b, v20
	v_exp_f32_e32 v29, v29
	v_mul_f32_e32 v26, v26, v28
	v_mul_f32_e32 v28, v31, v34
	v_mul_f32_e32 v27, v27, v28
	v_cvt_pk_bf16_f32 v24, v24, v25
	v_cvt_pk_bf16_f32 v25, v26, v27
	v_add_f32_e32 v26, 1.0, v29
	v_rcp_f32_e32 v26, v26
	v_mul_f32_e32 v27, 0xbfb8aa3b, v21
	v_exp_f32_e32 v27, v27
	global_store_dwordx2 v[32:33], v[24:25], off
	v_mul_f32_e32 v20, v20, v26
	v_mul_f32_e32 v16, v16, v20
	v_add_f32_e32 v20, 1.0, v27
	v_mul_f32_e32 v24, 0xbfb8aa3b, v22
	v_rcp_f32_e32 v20, v20
	v_exp_f32_e32 v24, v24
	v_mul_f32_e32 v25, 0xbfb8aa3b, v23
	v_exp_f32_e32 v25, v25
	v_mul_f32_e32 v20, v21, v20
	v_add_f32_e32 v21, 1.0, v24
	v_rcp_f32_e32 v21, v21
	v_add_f32_e32 v24, 1.0, v25
	v_rcp_f32_e32 v24, v24
	v_mul_f32_e32 v17, v17, v20
	v_mul_f32_e32 v20, v22, v21
	v_mul_f32_e32 v18, v18, v20
	v_mul_f32_e32 v20, v23, v24
	v_cvt_pk_bf16_f32 v16, v16, v17
	v_mul_f32_e32 v19, v19, v20
	v_cvt_pk_bf16_f32 v17, v18, v19
	global_store_dwordx2 v[32:33], v[16:17], off offset:128
	v_mul_f32_e32 v16, 0xbfb8aa3b, v12
	v_exp_f32_e32 v18, v16
	v_mul_f32_e32 v19, 0xbfb8aa3b, v13
	v_exp_f32_e32 v19, v19
	v_add_u32_e32 v16, 0xb0, v150
	v_add_f32_e32 v18, 1.0, v18
	v_rcp_f32_e32 v18, v18
	v_mad_i64_i32 v[16:17], vcc, v16, s70, v[140:141]
	v_lshl_add_u64 v[16:17], v[16:17], 0, v[142:143]
	v_mul_f32_e32 v12, v12, v18
	v_mul_f32_e32 v8, v8, v12
	v_add_f32_e32 v12, 1.0, v19
	v_mul_f32_e32 v18, 0xbfb8aa3b, v14
	v_rcp_f32_e32 v12, v12
	v_exp_f32_e32 v18, v18
	v_mul_f32_e32 v19, 0xbfb8aa3b, v15
	v_exp_f32_e32 v19, v19
	v_mul_f32_e32 v12, v13, v12
	v_add_f32_e32 v13, 1.0, v18
	v_rcp_f32_e32 v13, v13
	v_add_f32_e32 v18, 1.0, v19
	v_rcp_f32_e32 v18, v18
	v_mul_f32_e32 v9, v9, v12
	v_mul_f32_e32 v12, v14, v13
	v_mul_f32_e32 v13, 0xbfb8aa3b, v4
	v_exp_f32_e32 v13, v13
	v_mul_f32_e32 v10, v10, v12
	v_mul_f32_e32 v12, v15, v18
	v_mul_f32_e32 v11, v11, v12
	v_cvt_pk_bf16_f32 v8, v8, v9
	v_cvt_pk_bf16_f32 v9, v10, v11
	v_add_f32_e32 v10, 1.0, v13
	v_rcp_f32_e32 v10, v10
	v_mul_f32_e32 v11, 0xbfb8aa3b, v5
	v_exp_f32_e32 v11, v11
	global_store_dwordx2 v[16:17], v[8:9], off
	v_mul_f32_e32 v4, v4, v10
	v_mul_f32_e32 v0, v0, v4
	v_add_f32_e32 v4, 1.0, v11
	v_mul_f32_e32 v8, 0xbfb8aa3b, v6
	v_rcp_f32_e32 v4, v4
	v_exp_f32_e32 v8, v8
	v_mul_f32_e32 v9, 0xbfb8aa3b, v7
	v_exp_f32_e32 v9, v9
	v_mul_f32_e32 v4, v5, v4
	v_add_f32_e32 v5, 1.0, v8
	v_rcp_f32_e32 v5, v5
	v_add_f32_e32 v8, 1.0, v9
	v_rcp_f32_e32 v8, v8
	v_mul_f32_e32 v1, v1, v4
	v_mul_f32_e32 v4, v6, v5
	v_mul_f32_e32 v2, v2, v4
	v_mul_f32_e32 v4, v7, v8
	v_mul_f32_e32 v3, v3, v4
	v_cvt_pk_bf16_f32 v0, v0, v1
	v_cvt_pk_bf16_f32 v1, v2, v3
	global_store_dwordx2 v[16:17], v[0:1], off offset:128
	s_branch .LBB0_946

.Lov_11:
	v_mul_f32_e32 v151, 0xbfb8aa3b, v124
	v_exp_f32_e32 v151, v151
	v_mul_f32_e32 v154, 0xbfb8aa3b, v125
	v_exp_f32_e32 v154, v154
	v_lshl_or_b32 v142, s65, 7, v146
	v_add_f32_e32 v151, 1.0, v151
	v_rcp_f32_e32 v151, v151
	v_lshl_add_u32 v150, s44, 8, v144
	v_ashrrev_i32_e32 v143, 31, v142
	v_mov_b64_e32 v[140:141], s[22:23]
	v_mul_f32_e32 v124, v124, v151
	v_mul_f32_e32 v120, v120, v124
	v_add_f32_e32 v124, 1.0, v154
	v_mul_f32_e32 v151, 0xbfb8aa3b, v126
	v_rcp_f32_e32 v124, v124
	v_exp_f32_e32 v151, v151
	v_mul_f32_e32 v154, 0xbfb8aa3b, v127
	v_exp_f32_e32 v154, v154
	v_mul_f32_e32 v124, v125, v124
	v_add_f32_e32 v125, 1.0, v151
	v_rcp_f32_e32 v125, v125
	v_add_f32_e32 v151, 1.0, v154
	v_rcp_f32_e32 v151, v151
	v_mul_f32_e32 v121, v121, v124
	v_mul_f32_e32 v124, v126, v125
	v_mul_f32_e32 v125, 0xbfb8aa3b, v116
	v_exp_f32_e32 v125, v125
	v_mul_f32_e32 v122, v122, v124
	v_mul_f32_e32 v124, v127, v151
	v_mul_f32_e32 v123, v123, v124
	v_cvt_pk_bf16_f32 v120, v120, v121
	v_cvt_pk_bf16_f32 v121, v122, v123
	v_add_f32_e32 v122, 1.0, v125
	v_rcp_f32_e32 v122, v122
	v_mul_f32_e32 v123, 0xbfb8aa3b, v117
	v_exp_f32_e32 v123, v123
	v_mad_i64_i32 v[152:153], s[46:47], v150, s64, v[140:141]
	v_lshlrev_b64 v[142:143], 1, v[142:143]
	v_lshl_add_u64 v[152:153], v[152:153], 0, v[142:143]
	v_mul_f32_e32 v116, v116, v122
	global_store_dwordx2 v[152:153], v[120:121], off
	v_mul_f32_e32 v112, v112, v116
	v_add_f32_e32 v116, 1.0, v123
	v_mul_f32_e32 v120, 0xbfb8aa3b, v118
	v_rcp_f32_e32 v116, v116
	v_exp_f32_e32 v120, v120
	v_mul_f32_e32 v121, 0xbfb8aa3b, v119
	v_exp_f32_e32 v121, v121
	v_mul_f32_e32 v116, v117, v116
	v_add_f32_e32 v117, 1.0, v120
	v_rcp_f32_e32 v117, v117
	v_add_f32_e32 v120, 1.0, v121
	v_rcp_f32_e32 v120, v120
	v_mul_f32_e32 v113, v113, v116
	v_mul_f32_e32 v116, v118, v117
	v_mul_f32_e32 v114, v114, v116
	v_mul_f32_e32 v116, v119, v120
	v_cvt_pk_bf16_f32 v112, v112, v113
	v_mul_f32_e32 v115, v115, v116
	v_cvt_pk_bf16_f32 v113, v114, v115
	global_store_dwordx2 v[152:153], v[112:113], off offset:128
	v_mul_f32_e32 v112, 0xbfb8aa3b, v108
	v_exp_f32_e32 v114, v112
	v_mul_f32_e32 v115, 0xbfb8aa3b, v109
	v_exp_f32_e32 v115, v115
	v_or_b32_e32 v112, 16, v150
	v_add_f32_e32 v114, 1.0, v114
	v_rcp_f32_e32 v114, v114
	v_mad_i64_i32 v[112:113], s[46:47], v112, s64, v[140:141]
	v_lshl_add_u64 v[112:113], v[112:113], 0, v[142:143]
	v_mul_f32_e32 v108, v108, v114
	v_mul_f32_e32 v104, v104, v108
	v_add_f32_e32 v108, 1.0, v115
	v_mul_f32_e32 v114, 0xbfb8aa3b, v110
	v_rcp_f32_e32 v108, v108
	v_exp_f32_e32 v114, v114
	v_mul_f32_e32 v115, 0xbfb8aa3b, v111
	v_exp_f32_e32 v115, v115
	v_mul_f32_e32 v108, v109, v108
	v_add_f32_e32 v109, 1.0, v114
	v_rcp_f32_e32 v109, v109
	v_add_f32_e32 v114, 1.0, v115
	v_rcp_f32_e32 v114, v114
	v_mul_f32_e32 v105, v105, v108
	v_mul_f32_e32 v108, v110, v109
	v_mul_f32_e32 v109, 0xbfb8aa3b, v100
	v_exp_f32_e32 v109, v109
	v_mul_f32_e32 v106, v106, v108
	v_mul_f32_e32 v108, v111, v114
	v_mul_f32_e32 v107, v107, v108
	v_cvt_pk_bf16_f32 v104, v104, v105
	v_cvt_pk_bf16_f32 v105, v106, v107
	v_add_f32_e32 v106, 1.0, v109
	v_rcp_f32_e32 v106, v106
	v_mul_f32_e32 v107, 0xbfb8aa3b, v101
	v_exp_f32_e32 v107, v107
	global_store_dwordx2 v[112:113], v[104:105], off
	v_mul_f32_e32 v100, v100, v106
	v_mul_f32_e32 v96, v96, v100
	v_add_f32_e32 v100, 1.0, v107
	v_mul_f32_e32 v104, 0xbfb8aa3b, v102
	v_rcp_f32_e32 v100, v100
	v_exp_f32_e32 v104, v104
	v_mul_f32_e32 v105, 0xbfb8aa3b, v103
	v_exp_f32_e32 v105, v105
	v_mul_f32_e32 v100, v101, v100
	v_add_f32_e32 v101, 1.0, v104
	v_rcp_f32_e32 v101, v101
	v_add_f32_e32 v104, 1.0, v105
	v_rcp_f32_e32 v104, v104
	v_mul_f32_e32 v97, v97, v100
	v_mul_f32_e32 v100, v102, v101
	v_mul_f32_e32 v98, v98, v100
	v_mul_f32_e32 v100, v103, v104
	v_cvt_pk_bf16_f32 v96, v96, v97
	v_mul_f32_e32 v99, v99, v100
	v_cvt_pk_bf16_f32 v97, v98, v99
	global_store_dwordx2 v[112:113], v[96:97], off offset:128
	v_mul_f32_e32 v96, 0xbfb8aa3b, v92
	v_exp_f32_e32 v98, v96
	v_mul_f32_e32 v99, 0xbfb8aa3b, v93
	v_exp_f32_e32 v99, v99
	v_or_b32_e32 v96, 32, v150
	v_add_f32_e32 v98, 1.0, v98
	v_rcp_f32_e32 v98, v98
	v_mad_i64_i32 v[96:97], s[46:47], v96, s64, v[140:141]
	v_lshl_add_u64 v[96:97], v[96:97], 0, v[142:143]
	v_mul_f32_e32 v92, v92, v98
	v_mul_f32_e32 v88, v88, v92
	v_add_f32_e32 v92, 1.0, v99
	v_mul_f32_e32 v98, 0xbfb8aa3b, v94
	v_rcp_f32_e32 v92, v92
	v_exp_f32_e32 v98, v98
	v_mul_f32_e32 v99, 0xbfb8aa3b, v95
	v_exp_f32_e32 v99, v99
	v_mul_f32_e32 v92, v93, v92
	v_add_f32_e32 v93, 1.0, v98
	v_rcp_f32_e32 v93, v93
	v_add_f32_e32 v98, 1.0, v99
	v_rcp_f32_e32 v98, v98
	v_mul_f32_e32 v89, v89, v92
	v_mul_f32_e32 v92, v94, v93
	v_mul_f32_e32 v93, 0xbfb8aa3b, v84
	v_exp_f32_e32 v93, v93
	v_mul_f32_e32 v90, v90, v92
	v_mul_f32_e32 v92, v95, v98
	v_mul_f32_e32 v91, v91, v92
	v_cvt_pk_bf16_f32 v88, v88, v89
	v_cvt_pk_bf16_f32 v89, v90, v91
	v_add_f32_e32 v90, 1.0, v93
	v_rcp_f32_e32 v90, v90
	v_mul_f32_e32 v91, 0xbfb8aa3b, v85
	v_exp_f32_e32 v91, v91
	global_store_dwordx2 v[96:97], v[88:89], off
	v_mul_f32_e32 v84, v84, v90
	v_mul_f32_e32 v80, v80, v84
	v_add_f32_e32 v84, 1.0, v91
	v_mul_f32_e32 v88, 0xbfb8aa3b, v86
	v_rcp_f32_e32 v84, v84
	v_exp_f32_e32 v88, v88
	v_mul_f32_e32 v89, 0xbfb8aa3b, v87
	v_exp_f32_e32 v89, v89
	v_mul_f32_e32 v84, v85, v84
	v_add_f32_e32 v85, 1.0, v88
	v_rcp_f32_e32 v85, v85
	v_add_f32_e32 v88, 1.0, v89
	v_rcp_f32_e32 v88, v88
	v_mul_f32_e32 v81, v81, v84
	v_mul_f32_e32 v84, v86, v85
	v_mul_f32_e32 v82, v82, v84
	v_mul_f32_e32 v84, v87, v88
	v_cvt_pk_bf16_f32 v80, v80, v81
	v_mul_f32_e32 v83, v83, v84
	v_cvt_pk_bf16_f32 v81, v82, v83
	global_store_dwordx2 v[96:97], v[80:81], off offset:128
	v_mul_f32_e32 v80, 0xbfb8aa3b, v76
	v_exp_f32_e32 v82, v80
	v_mul_f32_e32 v83, 0xbfb8aa3b, v77
	v_exp_f32_e32 v83, v83
	v_or_b32_e32 v80, 48, v150
	v_add_f32_e32 v82, 1.0, v82
	v_rcp_f32_e32 v82, v82
	v_mad_i64_i32 v[80:81], s[46:47], v80, s64, v[140:141]
	v_lshl_add_u64 v[80:81], v[80:81], 0, v[142:143]
	v_mul_f32_e32 v76, v76, v82
	v_mul_f32_e32 v72, v72, v76
	v_add_f32_e32 v76, 1.0, v83
	v_mul_f32_e32 v82, 0xbfb8aa3b, v78
	v_rcp_f32_e32 v76, v76
	v_exp_f32_e32 v82, v82
	v_mul_f32_e32 v83, 0xbfb8aa3b, v79
	v_exp_f32_e32 v83, v83
	v_mul_f32_e32 v76, v77, v76
	v_add_f32_e32 v77, 1.0, v82
	v_rcp_f32_e32 v77, v77
	v_add_f32_e32 v82, 1.0, v83
	v_rcp_f32_e32 v82, v82
	v_mul_f32_e32 v73, v73, v76
	v_mul_f32_e32 v76, v78, v77
	v_mul_f32_e32 v77, 0xbfb8aa3b, v68
	v_exp_f32_e32 v77, v77
	v_mul_f32_e32 v74, v74, v76
	v_mul_f32_e32 v76, v79, v82
	v_mul_f32_e32 v75, v75, v76
	v_cvt_pk_bf16_f32 v72, v72, v73
	v_cvt_pk_bf16_f32 v73, v74, v75
	v_add_f32_e32 v74, 1.0, v77
	v_rcp_f32_e32 v74, v74
	v_mul_f32_e32 v75, 0xbfb8aa3b, v69
	v_exp_f32_e32 v75, v75
	global_store_dwordx2 v[80:81], v[72:73], off
	v_mul_f32_e32 v68, v68, v74
	v_mul_f32_e32 v64, v64, v68
	v_add_f32_e32 v68, 1.0, v75
	v_mul_f32_e32 v72, 0xbfb8aa3b, v70
	v_rcp_f32_e32 v68, v68
	v_exp_f32_e32 v72, v72
	v_mul_f32_e32 v73, 0xbfb8aa3b, v71
	v_exp_f32_e32 v73, v73
	v_mul_f32_e32 v68, v69, v68
	v_add_f32_e32 v69, 1.0, v72
	v_rcp_f32_e32 v69, v69
	v_add_f32_e32 v72, 1.0, v73
	v_rcp_f32_e32 v72, v72
	v_mul_f32_e32 v65, v65, v68
	v_mul_f32_e32 v68, v70, v69
	v_mul_f32_e32 v66, v66, v68
	v_mul_f32_e32 v68, v71, v72
	v_cvt_pk_bf16_f32 v64, v64, v65
	v_mul_f32_e32 v67, v67, v68
	v_cvt_pk_bf16_f32 v65, v66, v67
	global_store_dwordx2 v[80:81], v[64:65], off offset:128
	v_mov_b32_e32 v216, v140
	v_mov_b32_e32 v217, v141
	v_mov_b32_e32 v218, v142
	v_mov_b32_e32 v219, v143
	v_mov_b32_e32 v220, v150
	s_andn2_b64 vcc, exec, s[0:1]
	s_cbranch_vccnz .Lov_nb_11
	s_barrier
	v_mul_f32_e32 v64, 0xbfb8aa3b, v60
	v_exp_f32_e32 v66, v64
	v_mul_f32_e32 v67, 0xbfb8aa3b, v61
	v_exp_f32_e32 v67, v67
	v_add_u32_e32 v64, 0x80, v150
	v_add_f32_e32 v66, 1.0, v66
	v_rcp_f32_e32 v66, v66
	v_mad_i64_i32 v[64:65], vcc, v64, s64, v[140:141]
	v_lshl_add_u64 v[64:65], v[64:65], 0, v[142:143]
	v_mul_f32_e32 v60, v60, v66
	v_mul_f32_e32 v56, v56, v60
	v_add_f32_e32 v60, 1.0, v67
	v_mul_f32_e32 v66, 0xbfb8aa3b, v62
	v_rcp_f32_e32 v60, v60
	v_exp_f32_e32 v66, v66
	v_mul_f32_e32 v67, 0xbfb8aa3b, v63
	v_exp_f32_e32 v67, v67
	v_mul_f32_e32 v60, v61, v60
	v_add_f32_e32 v61, 1.0, v66
	v_rcp_f32_e32 v61, v61
	v_add_f32_e32 v66, 1.0, v67
	v_rcp_f32_e32 v66, v66
	v_mul_f32_e32 v57, v57, v60
	v_mul_f32_e32 v60, v62, v61
	v_mul_f32_e32 v61, 0xbfb8aa3b, v52
	v_exp_f32_e32 v61, v61
	v_mul_f32_e32 v58, v58, v60
	v_mul_f32_e32 v60, v63, v66
	v_mul_f32_e32 v59, v59, v60
	v_cvt_pk_bf16_f32 v56, v56, v57
	v_cvt_pk_bf16_f32 v57, v58, v59
	v_add_f32_e32 v58, 1.0, v61
	v_rcp_f32_e32 v58, v58
	v_mul_f32_e32 v59, 0xbfb8aa3b, v53
	v_exp_f32_e32 v59, v59
	global_store_dwordx2 v[64:65], v[56:57], off
	v_mul_f32_e32 v52, v52, v58
	v_mul_f32_e32 v48, v48, v52
	v_add_f32_e32 v52, 1.0, v59
	v_mul_f32_e32 v56, 0xbfb8aa3b, v54
	v_rcp_f32_e32 v52, v52
	v_exp_f32_e32 v56, v56
	v_mul_f32_e32 v57, 0xbfb8aa3b, v55
	v_exp_f32_e32 v57, v57
	v_mul_f32_e32 v52, v53, v52
	v_add_f32_e32 v53, 1.0, v56
	v_rcp_f32_e32 v53, v53
	v_add_f32_e32 v56, 1.0, v57
	v_rcp_f32_e32 v56, v56
	v_mul_f32_e32 v49, v49, v52
	v_mul_f32_e32 v52, v54, v53
	v_mul_f32_e32 v50, v50, v52
	v_mul_f32_e32 v52, v55, v56
	v_cvt_pk_bf16_f32 v48, v48, v49
	v_mul_f32_e32 v51, v51, v52
	v_cvt_pk_bf16_f32 v49, v50, v51
	global_store_dwordx2 v[64:65], v[48:49], off offset:128
	v_mul_f32_e32 v48, 0xbfb8aa3b, v44
	v_exp_f32_e32 v50, v48
	v_mul_f32_e32 v51, 0xbfb8aa3b, v45
	v_exp_f32_e32 v51, v51
	v_add_u32_e32 v48, 0x90, v150
	v_add_f32_e32 v50, 1.0, v50
	v_rcp_f32_e32 v50, v50
	v_mad_i64_i32 v[48:49], vcc, v48, s64, v[140:141]
	v_lshl_add_u64 v[48:49], v[48:49], 0, v[142:143]
	v_mul_f32_e32 v44, v44, v50
	v_mul_f32_e32 v40, v40, v44
	v_add_f32_e32 v44, 1.0, v51
	v_mul_f32_e32 v50, 0xbfb8aa3b, v46
	v_rcp_f32_e32 v44, v44
	v_exp_f32_e32 v50, v50
	v_mul_f32_e32 v51, 0xbfb8aa3b, v47
	v_exp_f32_e32 v51, v51
	v_mul_f32_e32 v44, v45, v44
	v_add_f32_e32 v45, 1.0, v50
	v_rcp_f32_e32 v45, v45
	v_add_f32_e32 v50, 1.0, v51
	v_rcp_f32_e32 v50, v50
	v_mul_f32_e32 v41, v41, v44
	v_mul_f32_e32 v44, v46, v45
	v_mul_f32_e32 v45, 0xbfb8aa3b, v36
	v_exp_f32_e32 v45, v45
	v_mul_f32_e32 v42, v42, v44
	v_mul_f32_e32 v44, v47, v50
	v_mul_f32_e32 v43, v43, v44
	v_cvt_pk_bf16_f32 v40, v40, v41
	v_cvt_pk_bf16_f32 v41, v42, v43
	v_add_f32_e32 v42, 1.0, v45
	v_rcp_f32_e32 v42, v42
	v_mul_f32_e32 v43, 0xbfb8aa3b, v37
	v_exp_f32_e32 v43, v43
	global_store_dwordx2 v[48:49], v[40:41], off
	v_mul_f32_e32 v36, v36, v42
	v_mul_f32_e32 v32, v32, v36
	v_add_f32_e32 v36, 1.0, v43
	v_mul_f32_e32 v40, 0xbfb8aa3b, v38
	v_rcp_f32_e32 v36, v36
	v_exp_f32_e32 v40, v40
	v_mul_f32_e32 v41, 0xbfb8aa3b, v39
	v_exp_f32_e32 v41, v41
	v_mul_f32_e32 v36, v37, v36
	v_add_f32_e32 v37, 1.0, v40
	v_rcp_f32_e32 v37, v37
	v_add_f32_e32 v40, 1.0, v41
	v_rcp_f32_e32 v40, v40
	v_mul_f32_e32 v33, v33, v36
	v_mul_f32_e32 v36, v38, v37
	v_mul_f32_e32 v34, v34, v36
	v_mul_f32_e32 v36, v39, v40
	v_cvt_pk_bf16_f32 v32, v32, v33
	v_mul_f32_e32 v35, v35, v36
	v_cvt_pk_bf16_f32 v33, v34, v35
	global_store_dwordx2 v[48:49], v[32:33], off offset:128
	v_mul_f32_e32 v32, 0xbfb8aa3b, v28
	v_exp_f32_e32 v34, v32
	v_mul_f32_e32 v35, 0xbfb8aa3b, v29
	v_exp_f32_e32 v35, v35
	v_add_u32_e32 v32, 0xa0, v150
	v_add_f32_e32 v34, 1.0, v34
	v_rcp_f32_e32 v34, v34
	v_mad_i64_i32 v[32:33], vcc, v32, s64, v[140:141]
	v_lshl_add_u64 v[32:33], v[32:33], 0, v[142:143]
	v_mul_f32_e32 v28, v28, v34
	v_mul_f32_e32 v24, v24, v28
	v_add_f32_e32 v28, 1.0, v35
	v_mul_f32_e32 v34, 0xbfb8aa3b, v30
	v_rcp_f32_e32 v28, v28
	v_exp_f32_e32 v34, v34
	v_mul_f32_e32 v35, 0xbfb8aa3b, v31
	v_exp_f32_e32 v35, v35
	v_mul_f32_e32 v28, v29, v28
	v_add_f32_e32 v29, 1.0, v34
	v_rcp_f32_e32 v29, v29
	v_add_f32_e32 v34, 1.0, v35
	v_rcp_f32_e32 v34, v34
	v_mul_f32_e32 v25, v25, v28
	v_mul_f32_e32 v28, v30, v29
	v_mul_f32_e32 v29, 0xbfb8aa3b, v20
	v_exp_f32_e32 v29, v29
	v_mul_f32_e32 v26, v26, v28
	v_mul_f32_e32 v28, v31, v34
	v_mul_f32_e32 v27, v27, v28
	v_cvt_pk_bf16_f32 v24, v24, v25
	v_cvt_pk_bf16_f32 v25, v26, v27
	v_add_f32_e32 v26, 1.0, v29
	v_rcp_f32_e32 v26, v26
	v_mul_f32_e32 v27, 0xbfb8aa3b, v21
	v_exp_f32_e32 v27, v27
	global_store_dwordx2 v[32:33], v[24:25], off
	v_mul_f32_e32 v20, v20, v26
	v_mul_f32_e32 v16, v16, v20
	v_add_f32_e32 v20, 1.0, v27
	v_mul_f32_e32 v24, 0xbfb8aa3b, v22
	v_rcp_f32_e32 v20, v20
	v_exp_f32_e32 v24, v24
	v_mul_f32_e32 v25, 0xbfb8aa3b, v23
	v_exp_f32_e32 v25, v25
	v_mul_f32_e32 v20, v21, v20
	v_add_f32_e32 v21, 1.0, v24
	v_rcp_f32_e32 v21, v21
	v_add_f32_e32 v24, 1.0, v25
	v_rcp_f32_e32 v24, v24
	v_mul_f32_e32 v17, v17, v20
	v_mul_f32_e32 v20, v22, v21
	v_mul_f32_e32 v18, v18, v20
	v_mul_f32_e32 v20, v23, v24
	v_cvt_pk_bf16_f32 v16, v16, v17
	v_mul_f32_e32 v19, v19, v20
	v_cvt_pk_bf16_f32 v17, v18, v19
	global_store_dwordx2 v[32:33], v[16:17], off offset:128
	v_mul_f32_e32 v16, 0xbfb8aa3b, v12
	v_exp_f32_e32 v18, v16
	v_mul_f32_e32 v19, 0xbfb8aa3b, v13
	v_exp_f32_e32 v19, v19
	v_add_u32_e32 v16, 0xb0, v150
	v_add_f32_e32 v18, 1.0, v18
	v_rcp_f32_e32 v18, v18
	v_mad_i64_i32 v[16:17], vcc, v16, s64, v[140:141]
	v_lshl_add_u64 v[16:17], v[16:17], 0, v[142:143]
	v_mul_f32_e32 v12, v12, v18
	v_mul_f32_e32 v8, v8, v12
	v_add_f32_e32 v12, 1.0, v19
	v_mul_f32_e32 v18, 0xbfb8aa3b, v14
	v_rcp_f32_e32 v12, v12
	v_exp_f32_e32 v18, v18
	v_mul_f32_e32 v19, 0xbfb8aa3b, v15
	v_exp_f32_e32 v19, v19
	v_mul_f32_e32 v12, v13, v12
	v_add_f32_e32 v13, 1.0, v18
	v_rcp_f32_e32 v13, v13
	v_add_f32_e32 v18, 1.0, v19
	v_rcp_f32_e32 v18, v18
	v_mul_f32_e32 v9, v9, v12
	v_mul_f32_e32 v12, v14, v13
	v_mul_f32_e32 v13, 0xbfb8aa3b, v4
	v_exp_f32_e32 v13, v13
	v_mul_f32_e32 v10, v10, v12
	v_mul_f32_e32 v12, v15, v18
	v_mul_f32_e32 v11, v11, v12
	v_cvt_pk_bf16_f32 v8, v8, v9
	v_cvt_pk_bf16_f32 v9, v10, v11
	v_add_f32_e32 v10, 1.0, v13
	v_rcp_f32_e32 v10, v10
	v_mul_f32_e32 v11, 0xbfb8aa3b, v5
	v_exp_f32_e32 v11, v11
	global_store_dwordx2 v[16:17], v[8:9], off
	v_mul_f32_e32 v4, v4, v10
	v_mul_f32_e32 v0, v0, v4
	v_add_f32_e32 v4, 1.0, v11
	v_mul_f32_e32 v8, 0xbfb8aa3b, v6
	v_rcp_f32_e32 v4, v4
	v_exp_f32_e32 v8, v8
	v_mul_f32_e32 v9, 0xbfb8aa3b, v7
	v_exp_f32_e32 v9, v9
	v_mul_f32_e32 v4, v5, v4
	v_add_f32_e32 v5, 1.0, v8
	v_rcp_f32_e32 v5, v5
	v_add_f32_e32 v8, 1.0, v9
	v_rcp_f32_e32 v8, v8
	v_mul_f32_e32 v1, v1, v4
	v_mul_f32_e32 v4, v6, v5
	v_mul_f32_e32 v2, v2, v4
	v_mul_f32_e32 v4, v7, v8
	v_mul_f32_e32 v3, v3, v4
	v_cvt_pk_bf16_f32 v0, v0, v1
	v_cvt_pk_bf16_f32 v1, v2, v3
	global_store_dwordx2 v[16:17], v[0:1], off offset:128
	s_branch .LBB0_1429
